# MLA: VALU stream paced one MFMA slot later (lag=1)
# baseline (speedup 1.0000x reference)
.Lmla_loop:
	s_waitcnt lgkmcnt(4)
	v_mfma_f32_32x32x16_bf16 v[66:81], v[138:141], v[98:101], v[122:137]
	ds_read_b128 v[138:141], v220 offset:13408
	v_exp_f32_e32 v34, v34
	v_exp_f32_e32 v35, v35
	v_exp_f32_e32 v36, v36
	v_mfma_f32_32x32x16_bf16 v[82:97], v[142:145], v[98:101], v[122:137]
	ds_read_b128 v[142:145], v220 offset:20064
	v_exp_f32_e32 v37, v37
	v_add_f32_e32 v231, v231, v34
	v_add_f32_e32 v232, v232, v35
	v_exp_f32_e32 v38, v38
	s_waitcnt lgkmcnt(4)
	v_mfma_f32_32x32x16_bf16 v[66:81], v[146:149], v[102:105], v[66:81]
	ds_read_b128 v[146:149], v220 offset:13440
	global_load_dwordx4 v[200:203], v226, s[4:5]
	global_load_dwordx4 v[204:207], v227, s[4:5]
	global_load_dwordx4 v[208:211], v228, s[4:5]
	s_add_u32 s4, s4, 0x6000
	s_addc_u32 s5, s5, 0
	global_load_dwordx4 v[212:215], v229, s[10:11]
	s_add_u32 s10, s10, 0x80
	s_addc_u32 s11, s11, 0
	v_exp_f32_e32 v39, v39
	v_add_f32_e32 v231, v231, v36
	v_add_f32_e32 v232, v232, v37
	v_mfma_f32_32x32x16_bf16 v[82:97], v[150:153], v[102:105], v[82:97]
	ds_read_b128 v[150:153], v220 offset:20096
	v_exp_f32_e32 v40, v40
	v_exp_f32_e32 v41, v41
	v_add_f32_e32 v231, v231, v38
	v_add_f32_e32 v232, v232, v39
	s_waitcnt lgkmcnt(4)
	v_mfma_f32_32x32x16_bf16 v[66:81], v[154:157], v[106:109], v[66:81]
	ds_read_b128 v[154:157], v220 offset:13472
	v_add_f32_e32 v231, v231, v40
	v_add_f32_e32 v232, v232, v41
	v_cvt_pk_bf16_f32 v34, v34, v35
	v_cvt_pk_bf16_f32 v35, v36, v37
	v_cvt_pk_bf16_f32 v36, v38, v39
	v_mfma_f32_32x32x16_bf16 v[82:97], v[158:161], v[106:109], v[82:97]
	ds_read_b128 v[158:161], v220 offset:20128
	v_cvt_pk_bf16_f32 v37, v40, v41
	v_exp_f32_e32 v42, v42
	v_exp_f32_e32 v43, v43
	s_waitcnt lgkmcnt(4)
	v_mfma_f32_32x32x16_bf16 v[66:81], v[138:141], v[110:113], v[66:81]
	ds_read_b128 v[162:165], v221 offset:0
	v_exp_f32_e32 v44, v44
	v_exp_f32_e32 v45, v45
	v_add_f32_e32 v231, v231, v42
	v_add_f32_e32 v232, v232, v43
	v_mfma_f32_32x32x16_bf16 v[82:97], v[142:145], v[110:113], v[82:97]
	ds_read_b128 v[166:169], v221 offset:4608
	v_exp_f32_e32 v46, v46
	v_exp_f32_e32 v47, v47
	v_add_f32_e32 v231, v231, v44
	s_waitcnt lgkmcnt(4)
	v_mfma_f32_32x32x16_bf16 v[66:81], v[146:149], v[114:117], v[66:81]
	ds_read_b128 v[170:173], v221 offset:32
	v_add_f32_e32 v232, v232, v45
	v_exp_f32_e32 v48, v48
	v_exp_f32_e32 v49, v49
	v_mfma_f32_32x32x16_bf16 v[82:97], v[150:153], v[114:117], v[82:97]
	ds_read_b128 v[174:177], v221 offset:4640
	v_add_f32_e32 v231, v231, v46
	v_add_f32_e32 v232, v232, v47
	v_add_f32_e32 v231, v231, v48
	v_add_f32_e32 v232, v232, v49
	v_cvt_pk_bf16_f32 v42, v42, v43
	v_cvt_pk_bf16_f32 v43, v44, v45
	s_waitcnt lgkmcnt(4)
	v_mfma_f32_32x32x16_bf16 v[66:81], v[154:157], v[118:121], v[66:81]
	ds_read_b128 v[180:183], v221 offset:64
	v_cvt_pk_bf16_f32 v44, v46, v47
	v_cvt_pk_bf16_f32 v45, v48, v49
	v_exp_f32_e32 v50, v50
	v_exp_f32_e32 v51, v51
	v_mfma_f32_32x32x16_bf16 v[82:97], v[158:161], v[118:121], v[82:97]
	ds_read_b128 v[184:187], v221 offset:4672
	v_exp_f32_e32 v52, v52
	v_exp_f32_e32 v53, v53
	s_waitcnt lgkmcnt(4)
	v_mfma_f32_32x32x16_bf16 v[2:17], v[162:165], v[34:37], v[2:17]
	ds_read_b128 v[188:191], v221 offset:96
	v_add_f32_e32 v231, v231, v50
	v_add_f32_e32 v232, v232, v51
	v_exp_f32_e32 v54, v54
	v_exp_f32_e32 v55, v55
	v_mfma_f32_32x32x16_bf16 v[18:33], v[166:169], v[34:37], v[18:33]
	ds_read_b128 v[192:195], v221 offset:4704
	v_add_f32_e32 v231, v231, v52
	v_add_f32_e32 v232, v232, v53
	v_exp_f32_e32 v56, v56
	v_exp_f32_e32 v57, v57
	s_waitcnt lgkmcnt(4)
	v_mfma_f32_32x32x16_bf16 v[2:17], v[170:173], v[42:45], v[2:17]
	v_add_f32_e32 v231, v231, v54
	v_add_f32_e32 v232, v232, v55
	v_add_f32_e32 v231, v231, v56
	v_add_f32_e32 v232, v232, v57
	v_mfma_f32_32x32x16_bf16 v[18:33], v[174:177], v[42:45], v[18:33]
	s_waitcnt vmcnt(4)
	ds_write_b64 v225, v[216:217] offset:18432
	ds_write_b64 v225, v[218:219] offset:18448
	v_cvt_pk_bf16_f32 v50, v50, v51
	v_cvt_pk_bf16_f32 v51, v52, v53
	v_cvt_pk_bf16_f32 v52, v54, v55
	v_cvt_pk_bf16_f32 v53, v56, v57
	v_exp_f32_e32 v58, v58
	s_waitcnt lgkmcnt(4)
	v_mfma_f32_32x32x16_bf16 v[2:17], v[180:183], v[50:53], v[2:17]
	v_exp_f32_e32 v59, v59
	v_exp_f32_e32 v60, v60
	v_exp_f32_e32 v61, v61
	v_mfma_f32_32x32x16_bf16 v[18:33], v[184:187], v[50:53], v[18:33]
	v_add_f32_e32 v231, v231, v58
	v_add_f32_e32 v232, v232, v59
	v_exp_f32_e32 v62, v62
	v_exp_f32_e32 v63, v63
	v_add_f32_e32 v231, v231, v60
	v_add_f32_e32 v232, v232, v61
	v_exp_f32_e32 v64, v64
	v_exp_f32_e32 v65, v65
	v_add_f32_e32 v231, v231, v62
	v_add_f32_e32 v232, v232, v63
	v_add_f32_e32 v231, v231, v64
	v_add_f32_e32 v232, v232, v65
	v_cvt_pk_bf16_f32 v58, v58, v59
	v_cvt_pk_bf16_f32 v59, v60, v61
	v_cvt_pk_bf16_f32 v60, v62, v63
	v_cvt_pk_bf16_f32 v61, v64, v65
	s_waitcnt lgkmcnt(2)
	s_nop 0
	v_mfma_f32_32x32x16_bf16 v[2:17], v[188:191], v[58:61], v[2:17]
	v_mfma_f32_32x32x16_bf16 v[18:33], v[192:195], v[58:61], v[18:33]
	ds_read_b128 v[138:141], v220 offset:26624
	ds_read_b128 v[142:145], v220 offset:33280
	ds_read_b128 v[146:149], v220 offset:26656
	ds_read_b128 v[150:153], v220 offset:33312
	ds_read_b128 v[154:157], v220 offset:26688
	ds_read_b128 v[158:161], v220 offset:33344
	s_waitcnt lgkmcnt(6)
	s_barrier
	s_waitcnt lgkmcnt(4)
	v_mfma_f32_32x32x16_bf16 v[34:49], v[138:141], v[98:101], v[122:137]
	ds_read_b128 v[138:141], v220 offset:26720
	v_exp_f32_e32 v66, v66
	v_exp_f32_e32 v67, v67
	v_exp_f32_e32 v68, v68
	v_mfma_f32_32x32x16_bf16 v[50:65], v[142:145], v[98:101], v[122:137]
	ds_read_b128 v[142:145], v220 offset:33376
	v_exp_f32_e32 v69, v69
	v_add_f32_e32 v231, v231, v66
	v_add_f32_e32 v232, v232, v67
	v_exp_f32_e32 v70, v70
	s_waitcnt lgkmcnt(4)
	v_mfma_f32_32x32x16_bf16 v[34:49], v[146:149], v[102:105], v[34:49]
	ds_read_b128 v[146:149], v220 offset:26752
	global_load_dwordx4 v[216:219], v229, s[10:11]
	s_add_u32 s10, s10, 0x80
	s_addc_u32 s11, s11, 0
	v_exp_f32_e32 v71, v71
	v_add_f32_e32 v231, v231, v68
	v_add_f32_e32 v232, v232, v69
	v_mfma_f32_32x32x16_bf16 v[50:65], v[150:153], v[102:105], v[50:65]
	ds_read_b128 v[150:153], v220 offset:33408
	v_exp_f32_e32 v72, v72
	v_exp_f32_e32 v73, v73
	v_add_f32_e32 v231, v231, v70
	v_add_f32_e32 v232, v232, v71
	s_waitcnt lgkmcnt(4)
	v_mfma_f32_32x32x16_bf16 v[34:49], v[154:157], v[106:109], v[34:49]
	ds_read_b128 v[154:157], v220 offset:26784
	v_add_f32_e32 v231, v231, v72
	v_add_f32_e32 v232, v232, v73
	v_cvt_pk_bf16_f32 v66, v66, v67
	v_cvt_pk_bf16_f32 v67, v68, v69
	v_cvt_pk_bf16_f32 v68, v70, v71
	v_mfma_f32_32x32x16_bf16 v[50:65], v[158:161], v[106:109], v[50:65]
	ds_read_b128 v[158:161], v220 offset:33440
	v_cvt_pk_bf16_f32 v69, v72, v73
	v_exp_f32_e32 v74, v74
	v_exp_f32_e32 v75, v75
	s_waitcnt lgkmcnt(4)
	v_mfma_f32_32x32x16_bf16 v[34:49], v[138:141], v[110:113], v[34:49]
	ds_read_b128 v[162:165], v221 offset:9216
	v_exp_f32_e32 v76, v76
	v_exp_f32_e32 v77, v77
	v_add_f32_e32 v231, v231, v74
	v_add_f32_e32 v232, v232, v75
	v_mfma_f32_32x32x16_bf16 v[50:65], v[142:145], v[110:113], v[50:65]
	ds_read_b128 v[166:169], v221 offset:13824
	v_exp_f32_e32 v78, v78
	v_exp_f32_e32 v79, v79
	v_add_f32_e32 v231, v231, v76
	s_waitcnt lgkmcnt(4)
	v_mfma_f32_32x32x16_bf16 v[34:49], v[146:149], v[114:117], v[34:49]
	ds_read_b128 v[170:173], v221 offset:9248
	v_add_f32_e32 v232, v232, v77
	v_exp_f32_e32 v80, v80
	v_exp_f32_e32 v81, v81
	v_mfma_f32_32x32x16_bf16 v[50:65], v[150:153], v[114:117], v[50:65]
	ds_read_b128 v[174:177], v221 offset:13856
	v_add_f32_e32 v231, v231, v78
	v_add_f32_e32 v232, v232, v79
	v_add_f32_e32 v231, v231, v80
	v_add_f32_e32 v232, v232, v81
	v_cvt_pk_bf16_f32 v74, v74, v75
	v_cvt_pk_bf16_f32 v75, v76, v77
	s_waitcnt lgkmcnt(4)
	v_mfma_f32_32x32x16_bf16 v[34:49], v[154:157], v[118:121], v[34:49]
	ds_read_b128 v[180:183], v221 offset:9280
	v_cvt_pk_bf16_f32 v76, v78, v79
	v_cvt_pk_bf16_f32 v77, v80, v81
	v_exp_f32_e32 v82, v82
	v_exp_f32_e32 v83, v83
	v_mfma_f32_32x32x16_bf16 v[50:65], v[158:161], v[118:121], v[50:65]
	ds_read_b128 v[184:187], v221 offset:13888
	v_exp_f32_e32 v84, v84
	v_exp_f32_e32 v85, v85
	s_waitcnt lgkmcnt(4)
	v_mfma_f32_32x32x16_bf16 v[2:17], v[162:165], v[66:69], v[2:17]
	ds_read_b128 v[188:191], v221 offset:9312
	v_add_f32_e32 v231, v231, v82
	v_add_f32_e32 v232, v232, v83
	v_exp_f32_e32 v86, v86
	v_exp_f32_e32 v87, v87
	v_mfma_f32_32x32x16_bf16 v[18:33], v[166:169], v[66:69], v[18:33]
	ds_read_b128 v[192:195], v221 offset:13920
	v_add_f32_e32 v231, v231, v84
	v_add_f32_e32 v232, v232, v85
	v_exp_f32_e32 v88, v88
	v_exp_f32_e32 v89, v89
	s_waitcnt lgkmcnt(4)
	v_mfma_f32_32x32x16_bf16 v[2:17], v[170:173], v[74:77], v[2:17]
	v_add_f32_e32 v231, v231, v86
	v_add_f32_e32 v232, v232, v87
	v_add_f32_e32 v231, v231, v88
	v_add_f32_e32 v232, v232, v89
	v_mfma_f32_32x32x16_bf16 v[18:33], v[174:177], v[74:77], v[18:33]
	s_waitcnt vmcnt(1)
	ds_write_b128 v222, v[200:203] offset:0
	ds_write_b128 v223, v[204:207] offset:0
	ds_write_b128 v224, v[208:211] offset:0
	ds_write_b64 v225, v[212:213] offset:27648
	ds_write_b64 v225, v[214:215] offset:27664
	v_cvt_pk_bf16_f32 v82, v82, v83
	v_cvt_pk_bf16_f32 v83, v84, v85
	v_cvt_pk_bf16_f32 v84, v86, v87
	v_cvt_pk_bf16_f32 v85, v88, v89
	v_exp_f32_e32 v90, v90
	s_waitcnt lgkmcnt(7)
	v_mfma_f32_32x32x16_bf16 v[2:17], v[180:183], v[82:85], v[2:17]
	v_exp_f32_e32 v91, v91
	v_exp_f32_e32 v92, v92
	v_exp_f32_e32 v93, v93
	v_mfma_f32_32x32x16_bf16 v[18:33], v[184:187], v[82:85], v[18:33]
	v_add_f32_e32 v231, v231, v90
	v_add_f32_e32 v232, v232, v91
	v_exp_f32_e32 v94, v94
	v_exp_f32_e32 v95, v95
	v_add_f32_e32 v231, v231, v92
	v_add_f32_e32 v232, v232, v93
	v_exp_f32_e32 v96, v96
	v_exp_f32_e32 v97, v97
	v_add_f32_e32 v231, v231, v94
	v_add_f32_e32 v232, v232, v95
	v_add_f32_e32 v231, v231, v96
	v_add_f32_e32 v232, v232, v97
	v_cvt_pk_bf16_f32 v90, v90, v91
	v_cvt_pk_bf16_f32 v91, v92, v93
	v_cvt_pk_bf16_f32 v92, v94, v95
	v_cvt_pk_bf16_f32 v93, v96, v97
	s_waitcnt lgkmcnt(5)
	s_nop 0
	v_mfma_f32_32x32x16_bf16 v[2:17], v[188:191], v[90:93], v[2:17]
	v_mfma_f32_32x32x16_bf16 v[18:33], v[192:195], v[90:93], v[18:33]
	ds_read_b128 v[138:141], v220 offset:39936
	ds_read_b128 v[142:145], v220 offset:46592
	ds_read_b128 v[146:149], v220 offset:39968
	ds_read_b128 v[150:153], v220 offset:46624
	ds_read_b128 v[154:157], v220 offset:40000
	ds_read_b128 v[158:161], v220 offset:46656
	s_waitcnt lgkmcnt(6)
	s_barrier
	s_waitcnt lgkmcnt(4)
	v_mfma_f32_32x32x16_bf16 v[66:81], v[138:141], v[98:101], v[122:137]
	ds_read_b128 v[138:141], v220 offset:40032
	v_exp_f32_e32 v34, v34
	v_exp_f32_e32 v35, v35
	v_exp_f32_e32 v36, v36
	v_mfma_f32_32x32x16_bf16 v[82:97], v[142:145], v[98:101], v[122:137]
	ds_read_b128 v[142:145], v220 offset:46688
	v_exp_f32_e32 v37, v37
	v_add_f32_e32 v231, v231, v34
	v_add_f32_e32 v232, v232, v35
	v_exp_f32_e32 v38, v38
	s_waitcnt lgkmcnt(4)
	v_mfma_f32_32x32x16_bf16 v[66:81], v[146:149], v[102:105], v[66:81]
	ds_read_b128 v[146:149], v220 offset:40064
	global_load_dwordx4 v[200:203], v226, s[4:5]
	global_load_dwordx4 v[204:207], v227, s[4:5]
	global_load_dwordx4 v[208:211], v228, s[4:5]
	s_add_u32 s4, s4, 0x6000
	s_addc_u32 s5, s5, 0
	global_load_dwordx4 v[212:215], v229, s[10:11]
	s_add_u32 s10, s10, 0x80
	s_addc_u32 s11, s11, 0
	v_exp_f32_e32 v39, v39
	v_add_f32_e32 v231, v231, v36
	v_add_f32_e32 v232, v232, v37
	v_mfma_f32_32x32x16_bf16 v[82:97], v[150:153], v[102:105], v[82:97]
	ds_read_b128 v[150:153], v220 offset:46720
	v_exp_f32_e32 v40, v40
	v_exp_f32_e32 v41, v41
	v_add_f32_e32 v231, v231, v38
	v_add_f32_e32 v232, v232, v39
	s_waitcnt lgkmcnt(4)
	v_mfma_f32_32x32x16_bf16 v[66:81], v[154:157], v[106:109], v[66:81]
	ds_read_b128 v[154:157], v220 offset:40096
	v_add_f32_e32 v231, v231, v40
	v_add_f32_e32 v232, v232, v41
	v_cvt_pk_bf16_f32 v34, v34, v35
	v_cvt_pk_bf16_f32 v35, v36, v37
	v_cvt_pk_bf16_f32 v36, v38, v39
	v_mfma_f32_32x32x16_bf16 v[82:97], v[158:161], v[106:109], v[82:97]
	ds_read_b128 v[158:161], v220 offset:46752
	v_cvt_pk_bf16_f32 v37, v40, v41
	v_exp_f32_e32 v42, v42
	v_exp_f32_e32 v43, v43
	s_waitcnt lgkmcnt(4)
	v_mfma_f32_32x32x16_bf16 v[66:81], v[138:141], v[110:113], v[66:81]
	ds_read_b128 v[162:165], v221 offset:18432
	v_exp_f32_e32 v44, v44
	v_exp_f32_e32 v45, v45
	v_add_f32_e32 v231, v231, v42
	v_add_f32_e32 v232, v232, v43
	v_mfma_f32_32x32x16_bf16 v[82:97], v[142:145], v[110:113], v[82:97]
	ds_read_b128 v[166:169], v221 offset:23040
	v_exp_f32_e32 v46, v46
	v_exp_f32_e32 v47, v47
	v_add_f32_e32 v231, v231, v44
	s_waitcnt lgkmcnt(4)
	v_mfma_f32_32x32x16_bf16 v[66:81], v[146:149], v[114:117], v[66:81]
	ds_read_b128 v[170:173], v221 offset:18464
	v_add_f32_e32 v232, v232, v45
	v_exp_f32_e32 v48, v48
	v_exp_f32_e32 v49, v49
	v_mfma_f32_32x32x16_bf16 v[82:97], v[150:153], v[114:117], v[82:97]
	ds_read_b128 v[174:177], v221 offset:23072
	v_add_f32_e32 v231, v231, v46
	v_add_f32_e32 v232, v232, v47
	v_add_f32_e32 v231, v231, v48
	v_add_f32_e32 v232, v232, v49
	v_cvt_pk_bf16_f32 v42, v42, v43
	v_cvt_pk_bf16_f32 v43, v44, v45
	s_waitcnt lgkmcnt(4)
	v_mfma_f32_32x32x16_bf16 v[66:81], v[154:157], v[118:121], v[66:81]
	ds_read_b128 v[180:183], v221 offset:18496
	v_cvt_pk_bf16_f32 v44, v46, v47
	v_cvt_pk_bf16_f32 v45, v48, v49
	v_exp_f32_e32 v50, v50
	v_exp_f32_e32 v51, v51
	v_mfma_f32_32x32x16_bf16 v[82:97], v[158:161], v[118:121], v[82:97]
	ds_read_b128 v[184:187], v221 offset:23104
	v_exp_f32_e32 v52, v52
	v_exp_f32_e32 v53, v53
	s_waitcnt lgkmcnt(4)
	v_mfma_f32_32x32x16_bf16 v[2:17], v[162:165], v[34:37], v[2:17]
	ds_read_b128 v[188:191], v221 offset:18528
	v_add_f32_e32 v231, v231, v50
	v_add_f32_e32 v232, v232, v51
	v_exp_f32_e32 v54, v54
	v_exp_f32_e32 v55, v55
	v_mfma_f32_32x32x16_bf16 v[18:33], v[166:169], v[34:37], v[18:33]
	ds_read_b128 v[192:195], v221 offset:23136
	v_add_f32_e32 v231, v231, v52
	v_add_f32_e32 v232, v232, v53
	v_exp_f32_e32 v56, v56
	v_exp_f32_e32 v57, v57
	s_waitcnt lgkmcnt(4)
	v_mfma_f32_32x32x16_bf16 v[2:17], v[170:173], v[42:45], v[2:17]
	v_add_f32_e32 v231, v231, v54
	v_add_f32_e32 v232, v232, v55
	v_add_f32_e32 v231, v231, v56
	v_add_f32_e32 v232, v232, v57
	v_mfma_f32_32x32x16_bf16 v[18:33], v[174:177], v[42:45], v[18:33]
	s_waitcnt vmcnt(4)
	ds_write_b64 v225, v[216:217] offset:0
	ds_write_b64 v225, v[218:219] offset:16
	v_cvt_pk_bf16_f32 v50, v50, v51
	v_cvt_pk_bf16_f32 v51, v52, v53
	v_cvt_pk_bf16_f32 v52, v54, v55
	v_cvt_pk_bf16_f32 v53, v56, v57
	v_exp_f32_e32 v58, v58
	s_waitcnt lgkmcnt(4)
	v_mfma_f32_32x32x16_bf16 v[2:17], v[180:183], v[50:53], v[2:17]
	v_exp_f32_e32 v59, v59
	v_exp_f32_e32 v60, v60
	v_exp_f32_e32 v61, v61
	v_mfma_f32_32x32x16_bf16 v[18:33], v[184:187], v[50:53], v[18:33]
	v_add_f32_e32 v231, v231, v58
	v_add_f32_e32 v232, v232, v59
	v_exp_f32_e32 v62, v62
	v_exp_f32_e32 v63, v63
	v_add_f32_e32 v231, v231, v60
	v_add_f32_e32 v232, v232, v61
	v_exp_f32_e32 v64, v64
	v_exp_f32_e32 v65, v65
	v_add_f32_e32 v231, v231, v62
	v_add_f32_e32 v232, v232, v63
	v_add_f32_e32 v231, v231, v64
	v_add_f32_e32 v232, v232, v65
	v_cvt_pk_bf16_f32 v58, v58, v59
	v_cvt_pk_bf16_f32 v59, v60, v61
	v_cvt_pk_bf16_f32 v60, v62, v63
	v_cvt_pk_bf16_f32 v61, v64, v65
	s_waitcnt lgkmcnt(2)
	s_nop 0
	v_mfma_f32_32x32x16_bf16 v[2:17], v[188:191], v[58:61], v[2:17]
	v_mfma_f32_32x32x16_bf16 v[18:33], v[192:195], v[58:61], v[18:33]
	ds_read_b128 v[138:141], v220 offset:0
	ds_read_b128 v[142:145], v220 offset:6656
	ds_read_b128 v[146:149], v220 offset:32
	ds_read_b128 v[150:153], v220 offset:6688
	ds_read_b128 v[154:157], v220 offset:64
	ds_read_b128 v[158:161], v220 offset:6720
	s_waitcnt lgkmcnt(6)
	s_barrier
	s_waitcnt lgkmcnt(4)
	v_mfma_f32_32x32x16_bf16 v[34:49], v[138:141], v[98:101], v[122:137]
	ds_read_b128 v[138:141], v220 offset:96
	v_exp_f32_e32 v66, v66
	v_exp_f32_e32 v67, v67
	v_exp_f32_e32 v68, v68
	v_mfma_f32_32x32x16_bf16 v[50:65], v[142:145], v[98:101], v[122:137]
	ds_read_b128 v[142:145], v220 offset:6752
	v_exp_f32_e32 v69, v69
	v_add_f32_e32 v231, v231, v66
	v_add_f32_e32 v232, v232, v67
	v_exp_f32_e32 v70, v70
	s_waitcnt lgkmcnt(4)
	v_mfma_f32_32x32x16_bf16 v[34:49], v[146:149], v[102:105], v[34:49]
	ds_read_b128 v[146:149], v220 offset:128
	global_load_dwordx4 v[216:219], v229, s[10:11]
	s_add_u32 s10, s10, 0x80
	s_addc_u32 s11, s11, 0
	v_exp_f32_e32 v71, v71
	v_add_f32_e32 v231, v231, v68
	v_add_f32_e32 v232, v232, v69
	v_mfma_f32_32x32x16_bf16 v[50:65], v[150:153], v[102:105], v[50:65]
	ds_read_b128 v[150:153], v220 offset:6784
	v_exp_f32_e32 v72, v72
	v_exp_f32_e32 v73, v73
	v_add_f32_e32 v231, v231, v70
	v_add_f32_e32 v232, v232, v71
	s_waitcnt lgkmcnt(4)
	v_mfma_f32_32x32x16_bf16 v[34:49], v[154:157], v[106:109], v[34:49]
	ds_read_b128 v[154:157], v220 offset:160
	v_add_f32_e32 v231, v231, v72
	v_add_f32_e32 v232, v232, v73
	v_cvt_pk_bf16_f32 v66, v66, v67
	v_cvt_pk_bf16_f32 v67, v68, v69
	v_cvt_pk_bf16_f32 v68, v70, v71
	v_mfma_f32_32x32x16_bf16 v[50:65], v[158:161], v[106:109], v[50:65]
	ds_read_b128 v[158:161], v220 offset:6816
	v_cvt_pk_bf16_f32 v69, v72, v73
	v_exp_f32_e32 v74, v74
	v_exp_f32_e32 v75, v75
	s_waitcnt lgkmcnt(4)
	v_mfma_f32_32x32x16_bf16 v[34:49], v[138:141], v[110:113], v[34:49]
	ds_read_b128 v[162:165], v221 offset:27648
	v_exp_f32_e32 v76, v76
	v_exp_f32_e32 v77, v77
	v_add_f32_e32 v231, v231, v74
	v_add_f32_e32 v232, v232, v75
	v_mfma_f32_32x32x16_bf16 v[50:65], v[142:145], v[110:113], v[50:65]
	ds_read_b128 v[166:169], v221 offset:32256
	v_exp_f32_e32 v78, v78
	v_exp_f32_e32 v79, v79
	v_add_f32_e32 v231, v231, v76
	s_waitcnt lgkmcnt(4)
	v_mfma_f32_32x32x16_bf16 v[34:49], v[146:149], v[114:117], v[34:49]
	ds_read_b128 v[170:173], v221 offset:27680
	v_add_f32_e32 v232, v232, v77
	v_exp_f32_e32 v80, v80
	v_exp_f32_e32 v81, v81
	v_mfma_f32_32x32x16_bf16 v[50:65], v[150:153], v[114:117], v[50:65]
	ds_read_b128 v[174:177], v221 offset:32288
	v_add_f32_e32 v231, v231, v78
	v_add_f32_e32 v232, v232, v79
	v_add_f32_e32 v231, v231, v80
	v_add_f32_e32 v232, v232, v81
	v_cvt_pk_bf16_f32 v74, v74, v75
	v_cvt_pk_bf16_f32 v75, v76, v77
	s_waitcnt lgkmcnt(4)
	v_mfma_f32_32x32x16_bf16 v[34:49], v[154:157], v[118:121], v[34:49]
	ds_read_b128 v[180:183], v221 offset:27712
	v_cvt_pk_bf16_f32 v76, v78, v79
	v_cvt_pk_bf16_f32 v77, v80, v81
	v_exp_f32_e32 v82, v82
	v_exp_f32_e32 v83, v83
	v_mfma_f32_32x32x16_bf16 v[50:65], v[158:161], v[118:121], v[50:65]
	ds_read_b128 v[184:187], v221 offset:32320
	v_exp_f32_e32 v84, v84
	v_exp_f32_e32 v85, v85
	s_waitcnt lgkmcnt(4)
	v_mfma_f32_32x32x16_bf16 v[2:17], v[162:165], v[66:69], v[2:17]
	ds_read_b128 v[188:191], v221 offset:27744
	v_add_f32_e32 v231, v231, v82
	v_add_f32_e32 v232, v232, v83
	v_exp_f32_e32 v86, v86
	v_exp_f32_e32 v87, v87
	v_mfma_f32_32x32x16_bf16 v[18:33], v[166:169], v[66:69], v[18:33]
	ds_read_b128 v[192:195], v221 offset:32352
	v_add_f32_e32 v231, v231, v84
	v_add_f32_e32 v232, v232, v85
	v_exp_f32_e32 v88, v88
	v_exp_f32_e32 v89, v89
	s_waitcnt lgkmcnt(4)
	v_mfma_f32_32x32x16_bf16 v[2:17], v[170:173], v[74:77], v[2:17]
	v_add_f32_e32 v231, v231, v86
	v_add_f32_e32 v232, v232, v87
	v_add_f32_e32 v231, v231, v88
	v_add_f32_e32 v232, v232, v89
	v_mfma_f32_32x32x16_bf16 v[18:33], v[174:177], v[74:77], v[18:33]
	s_waitcnt vmcnt(1)
	ds_write_b128 v222, v[200:203] offset:26624
	ds_write_b128 v223, v[204:207] offset:26624
	ds_write_b128 v224, v[208:211] offset:26624
	ds_write_b64 v225, v[212:213] offset:9216
	ds_write_b64 v225, v[214:215] offset:9232
	v_cvt_pk_bf16_f32 v82, v82, v83
	v_cvt_pk_bf16_f32 v83, v84, v85
	v_cvt_pk_bf16_f32 v84, v86, v87
	v_cvt_pk_bf16_f32 v85, v88, v89
	v_exp_f32_e32 v90, v90
	s_waitcnt lgkmcnt(7)
	v_mfma_f32_32x32x16_bf16 v[2:17], v[180:183], v[82:85], v[2:17]
	v_exp_f32_e32 v91, v91
	v_exp_f32_e32 v92, v92
	v_exp_f32_e32 v93, v93
	v_mfma_f32_32x32x16_bf16 v[18:33], v[184:187], v[82:85], v[18:33]
	v_add_f32_e32 v231, v231, v90
	v_add_f32_e32 v232, v232, v91
	v_exp_f32_e32 v94, v94
	v_exp_f32_e32 v95, v95
	v_add_f32_e32 v231, v231, v92
	v_add_f32_e32 v232, v232, v93
	v_exp_f32_e32 v96, v96
	v_exp_f32_e32 v97, v97
	v_add_f32_e32 v231, v231, v94
	v_add_f32_e32 v232, v232, v95
	v_add_f32_e32 v231, v231, v96
	v_add_f32_e32 v232, v232, v97
	v_cvt_pk_bf16_f32 v90, v90, v91
	v_cvt_pk_bf16_f32 v91, v92, v93
	v_cvt_pk_bf16_f32 v92, v94, v95
	v_cvt_pk_bf16_f32 v93, v96, v97
	s_waitcnt lgkmcnt(5)
	s_nop 0
	v_mfma_f32_32x32x16_bf16 v[2:17], v[188:191], v[90:93], v[2:17]
	v_mfma_f32_32x32x16_bf16 v[18:33], v[192:195], v[90:93], v[18:33]
	ds_read_b128 v[138:141], v220 offset:13312
	ds_read_b128 v[142:145], v220 offset:19968
	ds_read_b128 v[146:149], v220 offset:13344
	ds_read_b128 v[150:153], v220 offset:20000
	ds_read_b128 v[154:157], v220 offset:13376
	ds_read_b128 v[158:161], v220 offset:20032
	s_waitcnt lgkmcnt(6)
	s_barrier
	s_add_i32 s16, s16, -1
	s_cmp_lg_u32 s16, 0
	s_cbranch_scc1 .Lmla_loop
	s_waitcnt lgkmcnt(4)
	v_mfma_f32_32x32x16_bf16 v[66:81], v[138:141], v[98:101], v[122:137]
	ds_read_b128 v[138:141], v220 offset:13408
	v_exp_f32_e32 v34, v34
	v_exp_f32_e32 v35, v35
	v_exp_f32_e32 v36, v36
	v_mfma_f32_32x32x16_bf16 v[82:97], v[142:145], v[98:101], v[122:137]
	ds_read_b128 v[142:145], v220 offset:20064
	v_exp_f32_e32 v37, v37
	v_add_f32_e32 v231, v231, v34
	v_add_f32_e32 v232, v232, v35
	v_exp_f32_e32 v38, v38
	s_waitcnt lgkmcnt(4)
	v_mfma_f32_32x32x16_bf16 v[66:81], v[146:149], v[102:105], v[66:81]
	ds_read_b128 v[146:149], v220 offset:13440
	global_load_dwordx4 v[212:215], v229, s[10:11]
	s_add_u32 s10, s10, 0x80
	s_addc_u32 s11, s11, 0
	v_exp_f32_e32 v39, v39
	v_add_f32_e32 v231, v231, v36
	v_add_f32_e32 v232, v232, v37
	v_mfma_f32_32x32x16_bf16 v[82:97], v[150:153], v[102:105], v[82:97]
	ds_read_b128 v[150:153], v220 offset:20096
	v_exp_f32_e32 v40, v40
	v_exp_f32_e32 v41, v41
	v_add_f32_e32 v231, v231, v38
	v_add_f32_e32 v232, v232, v39
	s_waitcnt lgkmcnt(4)
	v_mfma_f32_32x32x16_bf16 v[66:81], v[154:157], v[106:109], v[66:81]
	ds_read_b128 v[154:157], v220 offset:13472
	v_add_f32_e32 v231, v231, v40
	v_add_f32_e32 v232, v232, v41
	v_cvt_pk_bf16_f32 v34, v34, v35
	v_cvt_pk_bf16_f32 v35, v36, v37
	v_cvt_pk_bf16_f32 v36, v38, v39
	v_mfma_f32_32x32x16_bf16 v[82:97], v[158:161], v[106:109], v[82:97]
	ds_read_b128 v[158:161], v220 offset:20128
	v_cvt_pk_bf16_f32 v37, v40, v41
	v_exp_f32_e32 v42, v42
	v_exp_f32_e32 v43, v43
	s_waitcnt lgkmcnt(4)
	v_mfma_f32_32x32x16_bf16 v[66:81], v[138:141], v[110:113], v[66:81]
	ds_read_b128 v[162:165], v221 offset:0
	v_exp_f32_e32 v44, v44
	v_exp_f32_e32 v45, v45
	v_add_f32_e32 v231, v231, v42
	v_add_f32_e32 v232, v232, v43
	v_mfma_f32_32x32x16_bf16 v[82:97], v[142:145], v[110:113], v[82:97]
	ds_read_b128 v[166:169], v221 offset:4608
	v_exp_f32_e32 v46, v46
	v_exp_f32_e32 v47, v47
	v_add_f32_e32 v231, v231, v44
	s_waitcnt lgkmcnt(4)
	v_mfma_f32_32x32x16_bf16 v[66:81], v[146:149], v[114:117], v[66:81]
	ds_read_b128 v[170:173], v221 offset:32
	v_add_f32_e32 v232, v232, v45
	v_exp_f32_e32 v48, v48
	v_exp_f32_e32 v49, v49
	v_mfma_f32_32x32x16_bf16 v[82:97], v[150:153], v[114:117], v[82:97]
	ds_read_b128 v[174:177], v221 offset:4640
	v_add_f32_e32 v231, v231, v46
	v_add_f32_e32 v232, v232, v47
	v_add_f32_e32 v231, v231, v48
	v_add_f32_e32 v232, v232, v49
	v_cvt_pk_bf16_f32 v42, v42, v43
	v_cvt_pk_bf16_f32 v43, v44, v45
	s_waitcnt lgkmcnt(4)
	v_mfma_f32_32x32x16_bf16 v[66:81], v[154:157], v[118:121], v[66:81]
	ds_read_b128 v[180:183], v221 offset:64
	v_cvt_pk_bf16_f32 v44, v46, v47
	v_cvt_pk_bf16_f32 v45, v48, v49
	v_exp_f32_e32 v50, v50
	v_exp_f32_e32 v51, v51
	v_mfma_f32_32x32x16_bf16 v[82:97], v[158:161], v[118:121], v[82:97]
	ds_read_b128 v[184:187], v221 offset:4672
	v_exp_f32_e32 v52, v52
	v_exp_f32_e32 v53, v53
	s_waitcnt lgkmcnt(4)
	v_mfma_f32_32x32x16_bf16 v[2:17], v[162:165], v[34:37], v[2:17]
	ds_read_b128 v[188:191], v221 offset:96
	v_add_f32_e32 v231, v231, v50
	v_add_f32_e32 v232, v232, v51
	v_exp_f32_e32 v54, v54
	v_exp_f32_e32 v55, v55
	v_mfma_f32_32x32x16_bf16 v[18:33], v[166:169], v[34:37], v[18:33]
	ds_read_b128 v[192:195], v221 offset:4704
	v_add_f32_e32 v231, v231, v52
	v_add_f32_e32 v232, v232, v53
	v_exp_f32_e32 v56, v56
	v_exp_f32_e32 v57, v57
	s_waitcnt lgkmcnt(4)
	v_mfma_f32_32x32x16_bf16 v[2:17], v[170:173], v[42:45], v[2:17]
	v_add_f32_e32 v231, v231, v54
	v_add_f32_e32 v232, v232, v55
	v_add_f32_e32 v231, v231, v56
	v_add_f32_e32 v232, v232, v57
	v_mfma_f32_32x32x16_bf16 v[18:33], v[174:177], v[42:45], v[18:33]
	s_waitcnt vmcnt(1)
	ds_write_b64 v225, v[216:217] offset:18432
	ds_write_b64 v225, v[218:219] offset:18448
	v_cvt_pk_bf16_f32 v50, v50, v51
	v_cvt_pk_bf16_f32 v51, v52, v53
	v_cvt_pk_bf16_f32 v52, v54, v55
	v_cvt_pk_bf16_f32 v53, v56, v57
	v_exp_f32_e32 v58, v58
	s_waitcnt lgkmcnt(4)
	v_mfma_f32_32x32x16_bf16 v[2:17], v[180:183], v[50:53], v[2:17]
	v_exp_f32_e32 v59, v59
	v_exp_f32_e32 v60, v60
	v_exp_f32_e32 v61, v61
	v_mfma_f32_32x32x16_bf16 v[18:33], v[184:187], v[50:53], v[18:33]
	v_add_f32_e32 v231, v231, v58
	v_add_f32_e32 v232, v232, v59
	v_exp_f32_e32 v62, v62
	v_exp_f32_e32 v63, v63
	v_add_f32_e32 v231, v231, v60
	v_add_f32_e32 v232, v232, v61
	v_exp_f32_e32 v64, v64
	v_exp_f32_e32 v65, v65
	v_add_f32_e32 v231, v231, v62
	v_add_f32_e32 v232, v232, v63
	v_add_f32_e32 v231, v231, v64
	v_add_f32_e32 v232, v232, v65
	v_cvt_pk_bf16_f32 v58, v58, v59
	v_cvt_pk_bf16_f32 v59, v60, v61
	v_cvt_pk_bf16_f32 v60, v62, v63
	v_cvt_pk_bf16_f32 v61, v64, v65
	s_waitcnt lgkmcnt(2)
	s_nop 0
	v_mfma_f32_32x32x16_bf16 v[2:17], v[188:191], v[58:61], v[2:17]
	v_mfma_f32_32x32x16_bf16 v[18:33], v[192:195], v[58:61], v[18:33]
	ds_read_b128 v[138:141], v220 offset:26624
	ds_read_b128 v[142:145], v220 offset:33280
	ds_read_b128 v[146:149], v220 offset:26656
	ds_read_b128 v[150:153], v220 offset:33312
	ds_read_b128 v[154:157], v220 offset:26688
	ds_read_b128 v[158:161], v220 offset:33344
	s_waitcnt lgkmcnt(6)
	s_barrier
	s_waitcnt lgkmcnt(4)
	v_mfma_f32_32x32x16_bf16 v[34:49], v[138:141], v[98:101], v[122:137]
	ds_read_b128 v[138:141], v220 offset:26720
	v_exp_f32_e32 v66, v66
	v_exp_f32_e32 v67, v67
	v_exp_f32_e32 v68, v68
	v_mfma_f32_32x32x16_bf16 v[50:65], v[142:145], v[98:101], v[122:137]
	ds_read_b128 v[142:145], v220 offset:33376
	v_exp_f32_e32 v69, v69
	v_add_f32_e32 v231, v231, v66
	v_add_f32_e32 v232, v232, v67
	v_exp_f32_e32 v70, v70
	s_waitcnt lgkmcnt(4)
	v_mfma_f32_32x32x16_bf16 v[34:49], v[146:149], v[102:105], v[34:49]
	ds_read_b128 v[146:149], v220 offset:26752
	v_exp_f32_e32 v71, v71
	v_add_f32_e32 v231, v231, v68
	v_add_f32_e32 v232, v232, v69
	v_mfma_f32_32x32x16_bf16 v[50:65], v[150:153], v[102:105], v[50:65]
	ds_read_b128 v[150:153], v220 offset:33408
	v_exp_f32_e32 v72, v72
	v_exp_f32_e32 v73, v73
	v_add_f32_e32 v231, v231, v70
	v_add_f32_e32 v232, v232, v71
	s_waitcnt lgkmcnt(4)
	v_mfma_f32_32x32x16_bf16 v[34:49], v[154:157], v[106:109], v[34:49]
	ds_read_b128 v[154:157], v220 offset:26784
	v_add_f32_e32 v231, v231, v72
	v_add_f32_e32 v232, v232, v73
	v_cvt_pk_bf16_f32 v66, v66, v67
	v_cvt_pk_bf16_f32 v67, v68, v69
	v_cvt_pk_bf16_f32 v68, v70, v71
	v_mfma_f32_32x32x16_bf16 v[50:65], v[158:161], v[106:109], v[50:65]
	ds_read_b128 v[158:161], v220 offset:33440
	v_cvt_pk_bf16_f32 v69, v72, v73
	v_exp_f32_e32 v74, v74
	v_exp_f32_e32 v75, v75
	s_waitcnt lgkmcnt(4)
	v_mfma_f32_32x32x16_bf16 v[34:49], v[138:141], v[110:113], v[34:49]
	ds_read_b128 v[162:165], v221 offset:9216
	v_exp_f32_e32 v76, v76
	v_exp_f32_e32 v77, v77
	v_add_f32_e32 v231, v231, v74
	v_add_f32_e32 v232, v232, v75
	v_mfma_f32_32x32x16_bf16 v[50:65], v[142:145], v[110:113], v[50:65]
	ds_read_b128 v[166:169], v221 offset:13824
	v_exp_f32_e32 v78, v78
	v_exp_f32_e32 v79, v79
	v_add_f32_e32 v231, v231, v76
	s_waitcnt lgkmcnt(4)
	v_mfma_f32_32x32x16_bf16 v[34:49], v[146:149], v[114:117], v[34:49]
	ds_read_b128 v[170:173], v221 offset:9248
	v_add_f32_e32 v232, v232, v77
	v_exp_f32_e32 v80, v80
	v_exp_f32_e32 v81, v81
	v_mfma_f32_32x32x16_bf16 v[50:65], v[150:153], v[114:117], v[50:65]
	ds_read_b128 v[174:177], v221 offset:13856
	v_add_f32_e32 v231, v231, v78
	v_add_f32_e32 v232, v232, v79
	v_add_f32_e32 v231, v231, v80
	v_add_f32_e32 v232, v232, v81
	v_cvt_pk_bf16_f32 v74, v74, v75
	v_cvt_pk_bf16_f32 v75, v76, v77
	s_waitcnt lgkmcnt(4)
	v_mfma_f32_32x32x16_bf16 v[34:49], v[154:157], v[118:121], v[34:49]
	ds_read_b128 v[180:183], v221 offset:9280
	v_cvt_pk_bf16_f32 v76, v78, v79
	v_cvt_pk_bf16_f32 v77, v80, v81
	v_exp_f32_e32 v82, v82
	v_exp_f32_e32 v83, v83
	v_mfma_f32_32x32x16_bf16 v[50:65], v[158:161], v[118:121], v[50:65]
	ds_read_b128 v[184:187], v221 offset:13888
	v_exp_f32_e32 v84, v84
	v_exp_f32_e32 v85, v85
	s_waitcnt lgkmcnt(4)
	v_mfma_f32_32x32x16_bf16 v[2:17], v[162:165], v[66:69], v[2:17]
	ds_read_b128 v[188:191], v221 offset:9312
	v_add_f32_e32 v231, v231, v82
	v_add_f32_e32 v232, v232, v83
	v_exp_f32_e32 v86, v86
	v_exp_f32_e32 v87, v87
	v_mfma_f32_32x32x16_bf16 v[18:33], v[166:169], v[66:69], v[18:33]
	ds_read_b128 v[192:195], v221 offset:13920
	v_add_f32_e32 v231, v231, v84
	v_add_f32_e32 v232, v232, v85
	v_exp_f32_e32 v88, v88
	v_exp_f32_e32 v89, v89
	s_waitcnt lgkmcnt(4)
	v_mfma_f32_32x32x16_bf16 v[2:17], v[170:173], v[74:77], v[2:17]
	v_add_f32_e32 v231, v231, v86
	v_add_f32_e32 v232, v232, v87
	v_add_f32_e32 v231, v231, v88
	v_add_f32_e32 v232, v232, v89
	v_mfma_f32_32x32x16_bf16 v[18:33], v[174:177], v[74:77], v[18:33]
	s_waitcnt vmcnt(0)
	ds_write_b64 v225, v[212:213] offset:27648
	ds_write_b64 v225, v[214:215] offset:27664
	v_cvt_pk_bf16_f32 v82, v82, v83
	v_cvt_pk_bf16_f32 v83, v84, v85
	v_cvt_pk_bf16_f32 v84, v86, v87
	v_cvt_pk_bf16_f32 v85, v88, v89
	v_exp_f32_e32 v90, v90
	s_waitcnt lgkmcnt(4)
	v_mfma_f32_32x32x16_bf16 v[2:17], v[180:183], v[82:85], v[2:17]
	v_exp_f32_e32 v91, v91
	v_exp_f32_e32 v92, v92
	v_exp_f32_e32 v93, v93
	v_mfma_f32_32x32x16_bf16 v[18:33], v[184:187], v[82:85], v[18:33]
	v_add_f32_e32 v231, v231, v90
	v_add_f32_e32 v232, v232, v91
	v_exp_f32_e32 v94, v94
	v_exp_f32_e32 v95, v95
	v_add_f32_e32 v231, v231, v92
	v_add_f32_e32 v232, v232, v93
	v_exp_f32_e32 v96, v96
	v_exp_f32_e32 v97, v97
	v_add_f32_e32 v231, v231, v94
	v_add_f32_e32 v232, v232, v95
	v_add_f32_e32 v231, v231, v96
	v_add_f32_e32 v232, v232, v97
	v_cvt_pk_bf16_f32 v90, v90, v91
	v_cvt_pk_bf16_f32 v91, v92, v93
	v_cvt_pk_bf16_f32 v92, v94, v95
	v_cvt_pk_bf16_f32 v93, v96, v97
	s_waitcnt lgkmcnt(2)
	s_nop 0
	v_mfma_f32_32x32x16_bf16 v[2:17], v[188:191], v[90:93], v[2:17]
	v_mfma_f32_32x32x16_bf16 v[18:33], v[192:195], v[90:93], v[18:33]
	ds_read_b128 v[138:141], v220 offset:39936
	ds_read_b128 v[142:145], v220 offset:46592
	ds_read_b128 v[146:149], v220 offset:39968
	ds_read_b128 v[150:153], v220 offset:46624
	ds_read_b128 v[154:157], v220 offset:40000
	ds_read_b128 v[158:161], v220 offset:46656
	s_waitcnt lgkmcnt(6)
	s_barrier
	global_load_dwordx2 v[200:201], v236, s[14:15] offset:0
	global_load_dwordx2 v[202:203], v236, s[14:15] offset:16
	global_load_dwordx2 v[204:205], v236, s[14:15] offset:32
	global_load_dwordx2 v[206:207], v236, s[14:15] offset:48
	global_load_dwordx2 v[208:209], v236, s[14:15] offset:64
	global_load_dwordx2 v[210:211], v236, s[14:15] offset:80
	global_load_dwordx2 v[212:213], v236, s[14:15] offset:96
	global_load_dwordx2 v[214:215], v236, s[14:15] offset:112
	s_waitcnt lgkmcnt(4)
	v_mfma_f32_32x32x16_bf16 v[66:81], v[138:141], v[98:101], v[122:137]
	ds_read_b128 v[138:141], v220 offset:40032
	v_exp_f32_e32 v34, v34
	v_exp_f32_e32 v35, v35
	v_exp_f32_e32 v36, v36
	v_mfma_f32_32x32x16_bf16 v[82:97], v[142:145], v[98:101], v[122:137]
	ds_read_b128 v[142:145], v220 offset:46688
	v_exp_f32_e32 v37, v37
	v_add_f32_e32 v231, v231, v34
	v_add_f32_e32 v232, v232, v35
	v_exp_f32_e32 v38, v38
	s_waitcnt lgkmcnt(4)
	v_mfma_f32_32x32x16_bf16 v[66:81], v[146:149], v[102:105], v[66:81]
	ds_read_b128 v[146:149], v220 offset:40064
	v_exp_f32_e32 v39, v39
	v_add_f32_e32 v231, v231, v36
	v_add_f32_e32 v232, v232, v37
	v_mfma_f32_32x32x16_bf16 v[82:97], v[150:153], v[102:105], v[82:97]
	ds_read_b128 v[150:153], v220 offset:46720
	v_exp_f32_e32 v40, v40
	v_exp_f32_e32 v41, v41
	v_add_f32_e32 v231, v231, v38
	v_add_f32_e32 v232, v232, v39
	s_waitcnt lgkmcnt(4)
	v_mfma_f32_32x32x16_bf16 v[66:81], v[154:157], v[106:109], v[66:81]
	ds_read_b128 v[154:157], v220 offset:40096
	v_add_f32_e32 v231, v231, v40
	v_add_f32_e32 v232, v232, v41
	v_cvt_pk_bf16_f32 v34, v34, v35
	v_cvt_pk_bf16_f32 v35, v36, v37
	v_cvt_pk_bf16_f32 v36, v38, v39
	v_mfma_f32_32x32x16_bf16 v[82:97], v[158:161], v[106:109], v[82:97]
	ds_read_b128 v[158:161], v220 offset:46752
	v_cvt_pk_bf16_f32 v37, v40, v41
	v_exp_f32_e32 v42, v42
	v_exp_f32_e32 v43, v43
	s_waitcnt lgkmcnt(4)
	v_mfma_f32_32x32x16_bf16 v[66:81], v[138:141], v[110:113], v[66:81]
	ds_read_b128 v[162:165], v221 offset:18432
	v_exp_f32_e32 v44, v44
	v_exp_f32_e32 v45, v45
	v_add_f32_e32 v231, v231, v42
	v_add_f32_e32 v232, v232, v43
	v_mfma_f32_32x32x16_bf16 v[82:97], v[142:145], v[110:113], v[82:97]
	ds_read_b128 v[166:169], v221 offset:23040
	v_exp_f32_e32 v46, v46
	v_exp_f32_e32 v47, v47
	v_add_f32_e32 v231, v231, v44
	s_waitcnt lgkmcnt(4)
	v_mfma_f32_32x32x16_bf16 v[66:81], v[146:149], v[114:117], v[66:81]
	ds_read_b128 v[170:173], v221 offset:18464
	v_add_f32_e32 v232, v232, v45
	v_exp_f32_e32 v48, v48
	v_exp_f32_e32 v49, v49
	v_mfma_f32_32x32x16_bf16 v[82:97], v[150:153], v[114:117], v[82:97]
	ds_read_b128 v[174:177], v221 offset:23072
	v_add_f32_e32 v231, v231, v46
	v_add_f32_e32 v232, v232, v47
	v_add_f32_e32 v231, v231, v48
	v_add_f32_e32 v232, v232, v49
	v_cvt_pk_bf16_f32 v42, v42, v43
	v_cvt_pk_bf16_f32 v43, v44, v45
	s_waitcnt lgkmcnt(4)
	v_mfma_f32_32x32x16_bf16 v[66:81], v[154:157], v[118:121], v[66:81]
	ds_read_b128 v[180:183], v221 offset:18496
	v_cvt_pk_bf16_f32 v44, v46, v47
	v_cvt_pk_bf16_f32 v45, v48, v49
	v_exp_f32_e32 v50, v50
	v_exp_f32_e32 v51, v51
	v_mfma_f32_32x32x16_bf16 v[82:97], v[158:161], v[118:121], v[82:97]
	ds_read_b128 v[184:187], v221 offset:23104
	v_exp_f32_e32 v52, v52
	v_exp_f32_e32 v53, v53
	s_waitcnt lgkmcnt(4)
	v_mfma_f32_32x32x16_bf16 v[2:17], v[162:165], v[34:37], v[2:17]
	ds_read_b128 v[188:191], v221 offset:18528
	v_add_f32_e32 v231, v231, v50
	v_add_f32_e32 v232, v232, v51
	v_exp_f32_e32 v54, v54
	v_exp_f32_e32 v55, v55
	v_mfma_f32_32x32x16_bf16 v[18:33], v[166:169], v[34:37], v[18:33]
	ds_read_b128 v[192:195], v221 offset:23136
	v_add_f32_e32 v231, v231, v52
	v_add_f32_e32 v232, v232, v53
	v_exp_f32_e32 v56, v56
	v_exp_f32_e32 v57, v57
	s_waitcnt lgkmcnt(4)
	v_mfma_f32_32x32x16_bf16 v[2:17], v[170:173], v[42:45], v[2:17]
	v_add_f32_e32 v231, v231, v54
	v_add_f32_e32 v232, v232, v55
	v_add_f32_e32 v231, v231, v56
	v_add_f32_e32 v232, v232, v57
	v_mfma_f32_32x32x16_bf16 v[18:33], v[174:177], v[42:45], v[18:33]
	v_cvt_pk_bf16_f32 v50, v50, v51
	v_cvt_pk_bf16_f32 v51, v52, v53
	v_cvt_pk_bf16_f32 v52, v54, v55
	v_cvt_pk_bf16_f32 v53, v56, v57
	v_exp_f32_e32 v58, v58
	s_waitcnt lgkmcnt(2)
	v_mfma_f32_32x32x16_bf16 v[2:17], v[180:183], v[50:53], v[2:17]
	v_exp_f32_e32 v59, v59
	v_exp_f32_e32 v60, v60
	v_exp_f32_e32 v61, v61
	v_mfma_f32_32x32x16_bf16 v[18:33], v[184:187], v[50:53], v[18:33]
	v_add_f32_e32 v231, v231, v58
	v_add_f32_e32 v232, v232, v59
	v_exp_f32_e32 v62, v62
	v_exp_f32_e32 v63, v63
	v_add_f32_e32 v231, v231, v60
	v_add_f32_e32 v232, v232, v61
	v_exp_f32_e32 v64, v64
	v_exp_f32_e32 v65, v65
	v_add_f32_e32 v231, v231, v62
	v_add_f32_e32 v232, v232, v63
	v_add_f32_e32 v231, v231, v64
	v_add_f32_e32 v232, v232, v65
	v_cvt_pk_bf16_f32 v58, v58, v59
	v_cvt_pk_bf16_f32 v59, v60, v61
	v_cvt_pk_bf16_f32 v60, v62, v63
	v_cvt_pk_bf16_f32 v61, v64, v65
	s_waitcnt lgkmcnt(0)
	s_nop 0
	v_mfma_f32_32x32x16_bf16 v[2:17], v[188:191], v[58:61], v[2:17]
	v_mfma_f32_32x32x16_bf16 v[18:33], v[192:195], v[58:61], v[18:33]
	s_waitcnt lgkmcnt(0)
	s_barrier
	s_mov_b64 s[24:25], s[14:15]
	s_add_i32 s2, s2, s88
	s_cmpk_lt_i32 s2, 0x200
	s_cbranch_scc0 .Lmla_nopf
	s_lshr_b32 s17, s2, 4
	s_and_b32 s18, s2, 15
	s_mul_i32 s19, s17, 0xcc000
	s_add_u32 s4, s78, s19
	s_addc_u32 s5, s79, 0
	s_mul_i32 s19, s17, 0x88000
	s_add_u32 s19, s19, 0x1a00000
	s_add_u32 s10, s78, s19
	s_addc_u32 s11, s79, 0
	s_lshl_b32 s19, s17, 12
	s_lshl_b32 s20, s18, 8
	s_add_u32 s19, s19, s20
	s_mul_i32 s19, s19, 0xc0
	s_add_u32 s19, s19, 0x1400000
	s_add_u32 s12, s80, s19
	s_addc_u32 s13, s81, 0
	s_lshr_b32 s19, s17, 3
	s_lshl_b32 s19, s19, 12
	s_add_u32 s19, s19, s20
	s_lshl_b32 s19, s19, 10
	s_and_b32 s21, s17, 7
	s_lshl_b32 s21, s21, 7
	s_add_u32 s19, s19, s21
	s_add_u32 s19, s19, 0x7900000
	s_add_u32 s14, s80, s19
	s_addc_u32 s15, s81, 0
	global_load_dwordx4 v[98:101], v237, s[12:13] offset:0
	global_load_dwordx4 v[102:105], v237, s[12:13] offset:32
	global_load_dwordx4 v[106:109], v237, s[12:13] offset:64
	global_load_dwordx4 v[110:113], v237, s[12:13] offset:96
	global_load_dwordx4 v[114:117], v237, s[12:13] offset:128
	global_load_dwordx4 v[118:121], v237, s[12:13] offset:160
	global_load_dwordx4 v[34:37], v226, s[4:5]
	global_load_dwordx4 v[38:41], v227, s[4:5]
	global_load_dwordx4 v[42:45], v228, s[4:5]
	global_load_dwordx4 v[46:49], v229, s[10:11]
	s_add_u32 s4, s4, 0x6000
	s_addc_u32 s5, s5, 0
	global_load_dwordx4 v[50:53], v226, s[4:5]
	global_load_dwordx4 v[54:57], v227, s[4:5]
	global_load_dwordx4 v[58:61], v228, s[4:5]
	global_load_dwordx4 v[62:65], v229, s[10:11] offset:128
	global_load_dwordx4 v[216:219], v229, s[10:11] offset:256
	s_add_u32 s4, s4, 0x6000
	s_addc_u32 s5, s5, 0
	s_add_u32 s10, s10, 0x180
	s_addc_u32 s11, s11, 0

.Lmls_loop:
	s_waitcnt lgkmcnt(4)
	v_mfma_f32_32x32x16_bf16 v[66:81], v[138:141], v[98:101], v[122:137]
	ds_read_b128 v[138:141], v220 offset:13408
	v_exp_f32_e32 v34, v34
	v_exp_f32_e32 v35, v35
	v_exp_f32_e32 v36, v36
	v_exp_f32_e32 v37, v37
	v_mfma_f32_32x32x16_bf16 v[82:97], v[142:145], v[98:101], v[122:137]
	ds_read_b128 v[142:145], v220 offset:20064
	v_add_f32_e32 v231, v231, v34
	v_add_f32_e32 v232, v232, v35
	v_exp_f32_e32 v38, v38
	v_exp_f32_e32 v39, v39
	s_waitcnt lgkmcnt(4)
	v_mfma_f32_32x32x16_bf16 v[66:81], v[146:149], v[102:105], v[66:81]
	ds_read_b128 v[146:149], v220 offset:13440
	global_load_dwordx4 v[200:203], v226, s[4:5]
	global_load_dwordx4 v[204:207], v227, s[4:5]
	global_load_dwordx4 v[208:211], v228, s[4:5]
	s_add_u32 s4, s4, 0x6000
	s_addc_u32 s5, s5, 0
	global_load_dwordx4 v[212:215], v229, s[10:11]
	s_add_u32 s10, s10, 0x80
	s_addc_u32 s11, s11, 0
	v_add_f32_e32 v231, v231, v36
	v_add_f32_e32 v232, v232, v37
	v_exp_f32_e32 v40, v40
	v_exp_f32_e32 v41, v41
	v_mfma_f32_32x32x16_bf16 v[82:97], v[150:153], v[102:105], v[82:97]
	ds_read_b128 v[150:153], v220 offset:20096
	v_add_f32_e32 v231, v231, v38
	v_add_f32_e32 v232, v232, v39
	v_add_f32_e32 v231, v231, v40
	v_add_f32_e32 v232, v232, v41
	v_cvt_pk_bf16_f32 v34, v34, v35
	v_cvt_pk_bf16_f32 v35, v36, v37
	s_waitcnt lgkmcnt(4)
	v_mfma_f32_32x32x16_bf16 v[66:81], v[154:157], v[106:109], v[66:81]
	ds_read_b128 v[154:157], v220 offset:13472
	v_cvt_pk_bf16_f32 v36, v38, v39
	v_cvt_pk_bf16_f32 v37, v40, v41
	v_exp_f32_e32 v42, v42
	v_exp_f32_e32 v43, v43
	v_mfma_f32_32x32x16_bf16 v[82:97], v[158:161], v[106:109], v[82:97]
	ds_read_b128 v[158:161], v220 offset:20128
	v_exp_f32_e32 v44, v44
	v_exp_f32_e32 v45, v45
	v_add_f32_e32 v231, v231, v42
	v_add_f32_e32 v232, v232, v43
	s_waitcnt lgkmcnt(4)
	v_mfma_f32_32x32x16_bf16 v[66:81], v[138:141], v[110:113], v[66:81]
	ds_read_b128 v[162:165], v221 offset:0
	v_exp_f32_e32 v46, v46
	v_exp_f32_e32 v47, v47
	v_add_f32_e32 v231, v231, v44
	v_add_f32_e32 v232, v232, v45
	v_exp_f32_e32 v48, v48
	v_mfma_f32_32x32x16_bf16 v[82:97], v[142:145], v[110:113], v[82:97]
	ds_read_b128 v[166:169], v221 offset:4608
	v_exp_f32_e32 v49, v49
	v_add_f32_e32 v231, v231, v46
	v_add_f32_e32 v232, v232, v47
	v_add_f32_e32 v231, v231, v48
	s_waitcnt lgkmcnt(4)
	v_mfma_f32_32x32x16_bf16 v[66:81], v[146:149], v[114:117], v[66:81]
	ds_read_b128 v[170:173], v221 offset:32
	v_add_f32_e32 v232, v232, v49
	v_cvt_pk_bf16_f32 v42, v42, v43
	v_cvt_pk_bf16_f32 v43, v44, v45
	v_cvt_pk_bf16_f32 v44, v46, v47
	v_cvt_pk_bf16_f32 v45, v48, v49
	v_exp_f32_e32 v50, v50
	v_mfma_f32_32x32x16_bf16 v[82:97], v[150:153], v[114:117], v[82:97]
	ds_read_b128 v[174:177], v221 offset:4640
	v_exp_f32_e32 v51, v51
	v_exp_f32_e32 v52, v52
	v_exp_f32_e32 v53, v53
	s_waitcnt lgkmcnt(4)
	v_mfma_f32_32x32x16_bf16 v[66:81], v[154:157], v[118:121], v[66:81]
	ds_read_b128 v[180:183], v221 offset:64
	v_add_f32_e32 v231, v231, v50
	v_add_f32_e32 v232, v232, v51
	v_exp_f32_e32 v54, v54
	v_exp_f32_e32 v55, v55
	v_mfma_f32_32x32x16_bf16 v[82:97], v[158:161], v[118:121], v[82:97]
	ds_read_b128 v[184:187], v221 offset:4672
	v_add_f32_e32 v231, v231, v52
	v_add_f32_e32 v232, v232, v53
	v_exp_f32_e32 v56, v56
	v_exp_f32_e32 v57, v57
	s_waitcnt lgkmcnt(4)
	v_mfma_f32_32x32x16_bf16 v[2:17], v[162:165], v[34:37], v[2:17]
	ds_read_b128 v[188:191], v221 offset:96
	v_add_f32_e32 v231, v231, v54
	v_add_f32_e32 v232, v232, v55
	v_add_f32_e32 v231, v231, v56
	v_add_f32_e32 v232, v232, v57
	v_cvt_pk_bf16_f32 v50, v50, v51
	v_cvt_pk_bf16_f32 v51, v52, v53
	v_cvt_pk_bf16_f32 v52, v54, v55
	v_mfma_f32_32x32x16_bf16 v[18:33], v[166:169], v[34:37], v[18:33]
	ds_read_b128 v[192:195], v221 offset:4704
	v_cvt_pk_bf16_f32 v53, v56, v57
	v_exp_f32_e32 v58, v58
	v_exp_f32_e32 v59, v59
	v_exp_f32_e32 v60, v60
	s_waitcnt lgkmcnt(4)
	v_mfma_f32_32x32x16_bf16 v[2:17], v[170:173], v[42:45], v[2:17]
	v_exp_f32_e32 v61, v61
	v_add_f32_e32 v231, v231, v58
	v_add_f32_e32 v232, v232, v59
	v_exp_f32_e32 v62, v62
	v_mfma_f32_32x32x16_bf16 v[18:33], v[174:177], v[42:45], v[18:33]
	s_waitcnt vmcnt(4)
	ds_write_b64 v225, v[216:217] offset:18432
	ds_write_b64 v225, v[218:219] offset:18448
	v_exp_f32_e32 v63, v63
	v_add_f32_e32 v231, v231, v60
	v_add_f32_e32 v232, v232, v61
	v_exp_f32_e32 v64, v64
	s_waitcnt lgkmcnt(4)
	v_mfma_f32_32x32x16_bf16 v[2:17], v[180:183], v[50:53], v[2:17]
	v_exp_f32_e32 v65, v65
	v_add_f32_e32 v231, v231, v62
	v_add_f32_e32 v232, v232, v63
	v_add_f32_e32 v231, v231, v64
	v_add_f32_e32 v232, v232, v65
	v_mfma_f32_32x32x16_bf16 v[18:33], v[184:187], v[50:53], v[18:33]
	v_cvt_pk_bf16_f32 v58, v58, v59
	v_cvt_pk_bf16_f32 v59, v60, v61
	v_cvt_pk_bf16_f32 v60, v62, v63
	v_cvt_pk_bf16_f32 v61, v64, v65
	v_max3_f32 v234, v66, v67, v68
	v_max3_f32 v235, v82, v83, v84
	s_waitcnt lgkmcnt(2)
	v_mfma_f32_32x32x16_bf16 v[2:17], v[188:191], v[58:61], v[2:17]
	v_max3_f32 v234, v234, v69, v70
	v_max3_f32 v235, v235, v85, v86
	v_max3_f32 v234, v234, v71, v72
	v_max3_f32 v235, v235, v87, v88
	v_max3_f32 v234, v234, v73, v74
	v_max3_f32 v235, v235, v89, v90
	v_max3_f32 v234, v234, v75, v76
	v_mfma_f32_32x32x16_bf16 v[18:33], v[192:195], v[58:61], v[18:33]
	v_max3_f32 v235, v235, v91, v92
	v_max3_f32 v234, v234, v77, v78
	v_max3_f32 v235, v235, v93, v94
	v_max3_f32 v234, v234, v79, v80
	v_max3_f32 v235, v235, v95, v96
	v_max3_f32 v234, v234, v81, v97
	v_max_f32_e32 v234, v234, v235
	v_mov_b32_e32 v235, v234
	s_nop 1
	v_permlane32_swap_b32_e32 v234, v235
	v_max_f32_e32 v233, v234, v235
	v_cmp_lt_f32_e32 vcc, 4.0, v233
	s_cbranch_vccz .Lmls_nr_p0
	s_nop 15
	v_max_f32_e32 v234, 0, v233
	v_exp_f32_e64 v235, -v234
	v_add_f32_e32 v230, v230, v234
	v_sub_f32_e32 v66, v66, v234
	v_sub_f32_e32 v67, v67, v234
	v_sub_f32_e32 v68, v68, v234
	v_sub_f32_e32 v69, v69, v234
	v_sub_f32_e32 v70, v70, v234
	v_sub_f32_e32 v71, v71, v234
	v_sub_f32_e32 v72, v72, v234
	v_sub_f32_e32 v73, v73, v234
	v_sub_f32_e32 v74, v74, v234
	v_sub_f32_e32 v75, v75, v234
	v_sub_f32_e32 v76, v76, v234
	v_sub_f32_e32 v77, v77, v234
	v_sub_f32_e32 v78, v78, v234
	v_sub_f32_e32 v79, v79, v234
	v_sub_f32_e32 v80, v80, v234
	v_sub_f32_e32 v81, v81, v234
	v_sub_f32_e32 v82, v82, v234
	v_sub_f32_e32 v83, v83, v234
	v_sub_f32_e32 v84, v84, v234
	v_sub_f32_e32 v85, v85, v234
	v_sub_f32_e32 v86, v86, v234
	v_sub_f32_e32 v87, v87, v234
	v_sub_f32_e32 v88, v88, v234
	v_sub_f32_e32 v89, v89, v234
	v_sub_f32_e32 v90, v90, v234
	v_sub_f32_e32 v91, v91, v234
	v_sub_f32_e32 v92, v92, v234
	v_sub_f32_e32 v93, v93, v234
	v_sub_f32_e32 v94, v94, v234
	v_sub_f32_e32 v95, v95, v234
	v_sub_f32_e32 v96, v96, v234
	v_sub_f32_e32 v97, v97, v234
	v_mul_f32_e32 v231, v231, v235
	v_mul_f32_e32 v232, v232, v235
	v_mul_f32_e32 v2, v2, v235
	v_mul_f32_e32 v3, v3, v235
	v_mul_f32_e32 v4, v4, v235
	v_mul_f32_e32 v5, v5, v235
	v_mul_f32_e32 v6, v6, v235
	v_mul_f32_e32 v7, v7, v235
	v_mul_f32_e32 v8, v8, v235
	v_mul_f32_e32 v9, v9, v235
	v_mul_f32_e32 v10, v10, v235
	v_mul_f32_e32 v11, v11, v235
	v_mul_f32_e32 v12, v12, v235
	v_mul_f32_e32 v13, v13, v235
	v_mul_f32_e32 v14, v14, v235
	v_mul_f32_e32 v15, v15, v235
	v_mul_f32_e32 v16, v16, v235
	v_mul_f32_e32 v17, v17, v235
	v_mul_f32_e32 v18, v18, v235
	v_mul_f32_e32 v19, v19, v235
	v_mul_f32_e32 v20, v20, v235
	v_mul_f32_e32 v21, v21, v235
	v_mul_f32_e32 v22, v22, v235
	v_mul_f32_e32 v23, v23, v235
	v_mul_f32_e32 v24, v24, v235
	v_mul_f32_e32 v25, v25, v235
	v_mul_f32_e32 v26, v26, v235
	v_mul_f32_e32 v27, v27, v235
	v_mul_f32_e32 v28, v28, v235
	v_mul_f32_e32 v29, v29, v235
	v_mul_f32_e32 v30, v30, v235
	v_mul_f32_e32 v31, v31, v235
	v_mul_f32_e32 v32, v32, v235
	v_mul_f32_e32 v33, v33, v235
	v_sub_f32_e32 v122, 0, v230
	v_mov_b32_e32 v123, v122
	v_mov_b32_e32 v124, v122
	v_mov_b32_e32 v125, v122
	v_mov_b32_e32 v126, v122
	v_mov_b32_e32 v127, v122
	v_mov_b32_e32 v128, v122
	v_mov_b32_e32 v129, v122
	v_mov_b32_e32 v130, v122
	v_mov_b32_e32 v131, v122
	v_mov_b32_e32 v132, v122
	v_mov_b32_e32 v133, v122
	v_mov_b32_e32 v134, v122
	v_mov_b32_e32 v135, v122
	v_mov_b32_e32 v136, v122
	v_mov_b32_e32 v137, v122
.Lmls_nr_p0:
	ds_read_b128 v[138:141], v220 offset:26624
	ds_read_b128 v[142:145], v220 offset:33280
	ds_read_b128 v[146:149], v220 offset:26656
	ds_read_b128 v[150:153], v220 offset:33312
	ds_read_b128 v[154:157], v220 offset:26688
	ds_read_b128 v[158:161], v220 offset:33344
	s_waitcnt lgkmcnt(6)
	s_barrier
	s_waitcnt lgkmcnt(4)
	v_mfma_f32_32x32x16_bf16 v[34:49], v[138:141], v[98:101], v[122:137]
	ds_read_b128 v[138:141], v220 offset:26720
	v_exp_f32_e32 v66, v66
	v_exp_f32_e32 v67, v67
	v_exp_f32_e32 v68, v68
	v_exp_f32_e32 v69, v69
	v_mfma_f32_32x32x16_bf16 v[50:65], v[142:145], v[98:101], v[122:137]
	ds_read_b128 v[142:145], v220 offset:33376
	v_add_f32_e32 v231, v231, v66
	v_add_f32_e32 v232, v232, v67
	v_exp_f32_e32 v70, v70
	v_exp_f32_e32 v71, v71
	s_waitcnt lgkmcnt(4)
	v_mfma_f32_32x32x16_bf16 v[34:49], v[146:149], v[102:105], v[34:49]
	ds_read_b128 v[146:149], v220 offset:26752
	global_load_dwordx4 v[216:219], v229, s[10:11]
	s_add_u32 s10, s10, 0x80
	s_addc_u32 s11, s11, 0
	v_add_f32_e32 v231, v231, v68
	v_add_f32_e32 v232, v232, v69
	v_exp_f32_e32 v72, v72
	v_exp_f32_e32 v73, v73
	v_mfma_f32_32x32x16_bf16 v[50:65], v[150:153], v[102:105], v[50:65]
	ds_read_b128 v[150:153], v220 offset:33408
	v_add_f32_e32 v231, v231, v70
	v_add_f32_e32 v232, v232, v71
	v_add_f32_e32 v231, v231, v72
	v_add_f32_e32 v232, v232, v73
	v_cvt_pk_bf16_f32 v66, v66, v67
	v_cvt_pk_bf16_f32 v67, v68, v69
	s_waitcnt lgkmcnt(4)
	v_mfma_f32_32x32x16_bf16 v[34:49], v[154:157], v[106:109], v[34:49]
	ds_read_b128 v[154:157], v220 offset:26784
	v_cvt_pk_bf16_f32 v68, v70, v71
	v_cvt_pk_bf16_f32 v69, v72, v73
	v_exp_f32_e32 v74, v74
	v_exp_f32_e32 v75, v75
	v_mfma_f32_32x32x16_bf16 v[50:65], v[158:161], v[106:109], v[50:65]
	ds_read_b128 v[158:161], v220 offset:33440
	v_exp_f32_e32 v76, v76
	v_exp_f32_e32 v77, v77
	v_add_f32_e32 v231, v231, v74
	v_add_f32_e32 v232, v232, v75
	s_waitcnt lgkmcnt(4)
	v_mfma_f32_32x32x16_bf16 v[34:49], v[138:141], v[110:113], v[34:49]
	ds_read_b128 v[162:165], v221 offset:9216
	v_exp_f32_e32 v78, v78
	v_exp_f32_e32 v79, v79
	v_add_f32_e32 v231, v231, v76
	v_add_f32_e32 v232, v232, v77
	v_exp_f32_e32 v80, v80
	v_mfma_f32_32x32x16_bf16 v[50:65], v[142:145], v[110:113], v[50:65]
	ds_read_b128 v[166:169], v221 offset:13824
	v_exp_f32_e32 v81, v81
	v_add_f32_e32 v231, v231, v78
	v_add_f32_e32 v232, v232, v79
	v_add_f32_e32 v231, v231, v80
	s_waitcnt lgkmcnt(4)
	v_mfma_f32_32x32x16_bf16 v[34:49], v[146:149], v[114:117], v[34:49]
	ds_read_b128 v[170:173], v221 offset:9248
	v_add_f32_e32 v232, v232, v81
	v_cvt_pk_bf16_f32 v74, v74, v75
	v_cvt_pk_bf16_f32 v75, v76, v77
	v_cvt_pk_bf16_f32 v76, v78, v79
	v_cvt_pk_bf16_f32 v77, v80, v81
	v_exp_f32_e32 v82, v82
	v_mfma_f32_32x32x16_bf16 v[50:65], v[150:153], v[114:117], v[50:65]
	ds_read_b128 v[174:177], v221 offset:13856
	v_exp_f32_e32 v83, v83
	v_exp_f32_e32 v84, v84
	v_exp_f32_e32 v85, v85
	s_waitcnt lgkmcnt(4)
	v_mfma_f32_32x32x16_bf16 v[34:49], v[154:157], v[118:121], v[34:49]
	ds_read_b128 v[180:183], v221 offset:9280
	v_add_f32_e32 v231, v231, v82
	v_add_f32_e32 v232, v232, v83
	v_exp_f32_e32 v86, v86
	v_exp_f32_e32 v87, v87
	v_mfma_f32_32x32x16_bf16 v[50:65], v[158:161], v[118:121], v[50:65]
	ds_read_b128 v[184:187], v221 offset:13888
	v_add_f32_e32 v231, v231, v84
	v_add_f32_e32 v232, v232, v85
	v_exp_f32_e32 v88, v88
	v_exp_f32_e32 v89, v89
	s_waitcnt lgkmcnt(4)
	v_mfma_f32_32x32x16_bf16 v[2:17], v[162:165], v[66:69], v[2:17]
	ds_read_b128 v[188:191], v221 offset:9312
	v_add_f32_e32 v231, v231, v86
	v_add_f32_e32 v232, v232, v87
	v_add_f32_e32 v231, v231, v88
	v_add_f32_e32 v232, v232, v89
	v_cvt_pk_bf16_f32 v82, v82, v83
	v_cvt_pk_bf16_f32 v83, v84, v85
	v_cvt_pk_bf16_f32 v84, v86, v87
	v_mfma_f32_32x32x16_bf16 v[18:33], v[166:169], v[66:69], v[18:33]
	ds_read_b128 v[192:195], v221 offset:13920
	v_cvt_pk_bf16_f32 v85, v88, v89
	v_exp_f32_e32 v90, v90
	v_exp_f32_e32 v91, v91
	v_exp_f32_e32 v92, v92
	s_waitcnt lgkmcnt(4)
	v_mfma_f32_32x32x16_bf16 v[2:17], v[170:173], v[74:77], v[2:17]
	v_exp_f32_e32 v93, v93
	v_add_f32_e32 v231, v231, v90
	v_add_f32_e32 v232, v232, v91
	v_exp_f32_e32 v94, v94
	v_mfma_f32_32x32x16_bf16 v[18:33], v[174:177], v[74:77], v[18:33]
	s_waitcnt vmcnt(1)
	ds_write_b128 v222, v[200:203] offset:0
	ds_write_b128 v223, v[204:207] offset:0
	ds_write_b128 v224, v[208:211] offset:0
	ds_write_b64 v225, v[212:213] offset:27648
	ds_write_b64 v225, v[214:215] offset:27664
	v_exp_f32_e32 v95, v95
	v_add_f32_e32 v231, v231, v92
	v_add_f32_e32 v232, v232, v93
	v_exp_f32_e32 v96, v96
	s_waitcnt lgkmcnt(7)
	v_mfma_f32_32x32x16_bf16 v[2:17], v[180:183], v[82:85], v[2:17]
	v_exp_f32_e32 v97, v97
	v_add_f32_e32 v231, v231, v94
	v_add_f32_e32 v232, v232, v95
	v_add_f32_e32 v231, v231, v96
	v_add_f32_e32 v232, v232, v97
	v_mfma_f32_32x32x16_bf16 v[18:33], v[184:187], v[82:85], v[18:33]
	v_cvt_pk_bf16_f32 v90, v90, v91
	v_cvt_pk_bf16_f32 v91, v92, v93
	v_cvt_pk_bf16_f32 v92, v94, v95
	v_cvt_pk_bf16_f32 v93, v96, v97
	v_max3_f32 v234, v34, v35, v36
	v_max3_f32 v235, v50, v51, v52
	s_waitcnt lgkmcnt(5)
	v_mfma_f32_32x32x16_bf16 v[2:17], v[188:191], v[90:93], v[2:17]
	v_max3_f32 v234, v234, v37, v38
	v_max3_f32 v235, v235, v53, v54
	v_max3_f32 v234, v234, v39, v40
	v_max3_f32 v235, v235, v55, v56
	v_max3_f32 v234, v234, v41, v42
	v_max3_f32 v235, v235, v57, v58
	v_max3_f32 v234, v234, v43, v44
	v_mfma_f32_32x32x16_bf16 v[18:33], v[192:195], v[90:93], v[18:33]
	v_max3_f32 v235, v235, v59, v60
	v_max3_f32 v234, v234, v45, v46
	v_max3_f32 v235, v235, v61, v62
	v_max3_f32 v234, v234, v47, v48
	v_max3_f32 v235, v235, v63, v64
	v_max3_f32 v234, v234, v49, v65
	v_max_f32_e32 v234, v234, v235
	v_mov_b32_e32 v235, v234
	s_nop 1
	v_permlane32_swap_b32_e32 v234, v235
	v_max_f32_e32 v233, v234, v235
	v_cmp_lt_f32_e32 vcc, 4.0, v233
	s_cbranch_vccz .Lmls_nr_p1
	s_nop 15
	v_max_f32_e32 v234, 0, v233
	v_exp_f32_e64 v235, -v234
	v_add_f32_e32 v230, v230, v234
	v_sub_f32_e32 v34, v34, v234
	v_sub_f32_e32 v35, v35, v234
	v_sub_f32_e32 v36, v36, v234
	v_sub_f32_e32 v37, v37, v234
	v_sub_f32_e32 v38, v38, v234
	v_sub_f32_e32 v39, v39, v234
	v_sub_f32_e32 v40, v40, v234
	v_sub_f32_e32 v41, v41, v234
	v_sub_f32_e32 v42, v42, v234
	v_sub_f32_e32 v43, v43, v234
	v_sub_f32_e32 v44, v44, v234
	v_sub_f32_e32 v45, v45, v234
	v_sub_f32_e32 v46, v46, v234
	v_sub_f32_e32 v47, v47, v234
	v_sub_f32_e32 v48, v48, v234
	v_sub_f32_e32 v49, v49, v234
	v_sub_f32_e32 v50, v50, v234
	v_sub_f32_e32 v51, v51, v234
	v_sub_f32_e32 v52, v52, v234
	v_sub_f32_e32 v53, v53, v234
	v_sub_f32_e32 v54, v54, v234
	v_sub_f32_e32 v55, v55, v234
	v_sub_f32_e32 v56, v56, v234
	v_sub_f32_e32 v57, v57, v234
	v_sub_f32_e32 v58, v58, v234
	v_sub_f32_e32 v59, v59, v234
	v_sub_f32_e32 v60, v60, v234
	v_sub_f32_e32 v61, v61, v234
	v_sub_f32_e32 v62, v62, v234
	v_sub_f32_e32 v63, v63, v234
	v_sub_f32_e32 v64, v64, v234
	v_sub_f32_e32 v65, v65, v234
	v_mul_f32_e32 v231, v231, v235
	v_mul_f32_e32 v232, v232, v235
	v_mul_f32_e32 v2, v2, v235
	v_mul_f32_e32 v3, v3, v235
	v_mul_f32_e32 v4, v4, v235
	v_mul_f32_e32 v5, v5, v235
	v_mul_f32_e32 v6, v6, v235
	v_mul_f32_e32 v7, v7, v235
	v_mul_f32_e32 v8, v8, v235
	v_mul_f32_e32 v9, v9, v235
	v_mul_f32_e32 v10, v10, v235
	v_mul_f32_e32 v11, v11, v235
	v_mul_f32_e32 v12, v12, v235
	v_mul_f32_e32 v13, v13, v235
	v_mul_f32_e32 v14, v14, v235
	v_mul_f32_e32 v15, v15, v235
	v_mul_f32_e32 v16, v16, v235
	v_mul_f32_e32 v17, v17, v235
	v_mul_f32_e32 v18, v18, v235
	v_mul_f32_e32 v19, v19, v235
	v_mul_f32_e32 v20, v20, v235
	v_mul_f32_e32 v21, v21, v235
	v_mul_f32_e32 v22, v22, v235
	v_mul_f32_e32 v23, v23, v235
	v_mul_f32_e32 v24, v24, v235
	v_mul_f32_e32 v25, v25, v235
	v_mul_f32_e32 v26, v26, v235
	v_mul_f32_e32 v27, v27, v235
	v_mul_f32_e32 v28, v28, v235
	v_mul_f32_e32 v29, v29, v235
	v_mul_f32_e32 v30, v30, v235
	v_mul_f32_e32 v31, v31, v235
	v_mul_f32_e32 v32, v32, v235
	v_mul_f32_e32 v33, v33, v235
	v_sub_f32_e32 v122, 0, v230
	v_mov_b32_e32 v123, v122
	v_mov_b32_e32 v124, v122
	v_mov_b32_e32 v125, v122
	v_mov_b32_e32 v126, v122
	v_mov_b32_e32 v127, v122
	v_mov_b32_e32 v128, v122
	v_mov_b32_e32 v129, v122
	v_mov_b32_e32 v130, v122
	v_mov_b32_e32 v131, v122
	v_mov_b32_e32 v132, v122
	v_mov_b32_e32 v133, v122
	v_mov_b32_e32 v134, v122
	v_mov_b32_e32 v135, v122
	v_mov_b32_e32 v136, v122
	v_mov_b32_e32 v137, v122
.Lmls_nr_p1:
	ds_read_b128 v[138:141], v220 offset:39936
	ds_read_b128 v[142:145], v220 offset:46592
	ds_read_b128 v[146:149], v220 offset:39968
	ds_read_b128 v[150:153], v220 offset:46624
	ds_read_b128 v[154:157], v220 offset:40000
	ds_read_b128 v[158:161], v220 offset:46656
	s_waitcnt lgkmcnt(6)
	s_barrier
	s_waitcnt lgkmcnt(4)
	v_mfma_f32_32x32x16_bf16 v[66:81], v[138:141], v[98:101], v[122:137]
	ds_read_b128 v[138:141], v220 offset:40032
	v_exp_f32_e32 v34, v34
	v_exp_f32_e32 v35, v35
	v_exp_f32_e32 v36, v36
	v_exp_f32_e32 v37, v37
	v_mfma_f32_32x32x16_bf16 v[82:97], v[142:145], v[98:101], v[122:137]
	ds_read_b128 v[142:145], v220 offset:46688
	v_add_f32_e32 v231, v231, v34
	v_add_f32_e32 v232, v232, v35
	v_exp_f32_e32 v38, v38
	v_exp_f32_e32 v39, v39
	s_waitcnt lgkmcnt(4)
	v_mfma_f32_32x32x16_bf16 v[66:81], v[146:149], v[102:105], v[66:81]
	ds_read_b128 v[146:149], v220 offset:40064
	global_load_dwordx4 v[200:203], v226, s[4:5]
	global_load_dwordx4 v[204:207], v227, s[4:5]
	global_load_dwordx4 v[208:211], v228, s[4:5]
	s_add_u32 s4, s4, 0x6000
	s_addc_u32 s5, s5, 0
	global_load_dwordx4 v[212:215], v229, s[10:11]
	s_add_u32 s10, s10, 0x80
	s_addc_u32 s11, s11, 0
	v_add_f32_e32 v231, v231, v36
	v_add_f32_e32 v232, v232, v37
	v_exp_f32_e32 v40, v40
	v_exp_f32_e32 v41, v41
	v_mfma_f32_32x32x16_bf16 v[82:97], v[150:153], v[102:105], v[82:97]
	ds_read_b128 v[150:153], v220 offset:46720
	v_add_f32_e32 v231, v231, v38
	v_add_f32_e32 v232, v232, v39
	v_add_f32_e32 v231, v231, v40
	v_add_f32_e32 v232, v232, v41
	v_cvt_pk_bf16_f32 v34, v34, v35
	v_cvt_pk_bf16_f32 v35, v36, v37
	s_waitcnt lgkmcnt(4)
	v_mfma_f32_32x32x16_bf16 v[66:81], v[154:157], v[106:109], v[66:81]
	ds_read_b128 v[154:157], v220 offset:40096
	v_cvt_pk_bf16_f32 v36, v38, v39
	v_cvt_pk_bf16_f32 v37, v40, v41
	v_exp_f32_e32 v42, v42
	v_exp_f32_e32 v43, v43
	v_mfma_f32_32x32x16_bf16 v[82:97], v[158:161], v[106:109], v[82:97]
	ds_read_b128 v[158:161], v220 offset:46752
	v_exp_f32_e32 v44, v44
	v_exp_f32_e32 v45, v45
	v_add_f32_e32 v231, v231, v42
	v_add_f32_e32 v232, v232, v43
	s_waitcnt lgkmcnt(4)
	v_mfma_f32_32x32x16_bf16 v[66:81], v[138:141], v[110:113], v[66:81]
	ds_read_b128 v[162:165], v221 offset:18432
	v_exp_f32_e32 v46, v46
	v_exp_f32_e32 v47, v47
	v_add_f32_e32 v231, v231, v44
	v_add_f32_e32 v232, v232, v45
	v_exp_f32_e32 v48, v48
	v_mfma_f32_32x32x16_bf16 v[82:97], v[142:145], v[110:113], v[82:97]
	ds_read_b128 v[166:169], v221 offset:23040
	v_exp_f32_e32 v49, v49
	v_add_f32_e32 v231, v231, v46
	v_add_f32_e32 v232, v232, v47
	v_add_f32_e32 v231, v231, v48
	s_waitcnt lgkmcnt(4)
	v_mfma_f32_32x32x16_bf16 v[66:81], v[146:149], v[114:117], v[66:81]
	ds_read_b128 v[170:173], v221 offset:18464
	v_add_f32_e32 v232, v232, v49
	v_cvt_pk_bf16_f32 v42, v42, v43
	v_cvt_pk_bf16_f32 v43, v44, v45
	v_cvt_pk_bf16_f32 v44, v46, v47
	v_cvt_pk_bf16_f32 v45, v48, v49
	v_exp_f32_e32 v50, v50
	v_mfma_f32_32x32x16_bf16 v[82:97], v[150:153], v[114:117], v[82:97]
	ds_read_b128 v[174:177], v221 offset:23072
	v_exp_f32_e32 v51, v51
	v_exp_f32_e32 v52, v52
	v_exp_f32_e32 v53, v53
	s_waitcnt lgkmcnt(4)
	v_mfma_f32_32x32x16_bf16 v[66:81], v[154:157], v[118:121], v[66:81]
	ds_read_b128 v[180:183], v221 offset:18496
	v_add_f32_e32 v231, v231, v50
	v_add_f32_e32 v232, v232, v51
	v_exp_f32_e32 v54, v54
	v_exp_f32_e32 v55, v55
	v_mfma_f32_32x32x16_bf16 v[82:97], v[158:161], v[118:121], v[82:97]
	ds_read_b128 v[184:187], v221 offset:23104
	v_add_f32_e32 v231, v231, v52
	v_add_f32_e32 v232, v232, v53
	v_exp_f32_e32 v56, v56
	v_exp_f32_e32 v57, v57
	s_waitcnt lgkmcnt(4)
	v_mfma_f32_32x32x16_bf16 v[2:17], v[162:165], v[34:37], v[2:17]
	ds_read_b128 v[188:191], v221 offset:18528
	v_add_f32_e32 v231, v231, v54
	v_add_f32_e32 v232, v232, v55
	v_add_f32_e32 v231, v231, v56
	v_add_f32_e32 v232, v232, v57
	v_cvt_pk_bf16_f32 v50, v50, v51
	v_cvt_pk_bf16_f32 v51, v52, v53
	v_cvt_pk_bf16_f32 v52, v54, v55
	v_mfma_f32_32x32x16_bf16 v[18:33], v[166:169], v[34:37], v[18:33]
	ds_read_b128 v[192:195], v221 offset:23136
	v_cvt_pk_bf16_f32 v53, v56, v57
	v_exp_f32_e32 v58, v58
	v_exp_f32_e32 v59, v59
	v_exp_f32_e32 v60, v60
	s_waitcnt lgkmcnt(4)
	v_mfma_f32_32x32x16_bf16 v[2:17], v[170:173], v[42:45], v[2:17]
	v_exp_f32_e32 v61, v61
	v_add_f32_e32 v231, v231, v58
	v_add_f32_e32 v232, v232, v59
	v_exp_f32_e32 v62, v62
	v_mfma_f32_32x32x16_bf16 v[18:33], v[174:177], v[42:45], v[18:33]
	s_waitcnt vmcnt(4)
	ds_write_b64 v225, v[216:217] offset:0
	ds_write_b64 v225, v[218:219] offset:16
	v_exp_f32_e32 v63, v63
	v_add_f32_e32 v231, v231, v60
	v_add_f32_e32 v232, v232, v61
	v_exp_f32_e32 v64, v64
	s_waitcnt lgkmcnt(4)
	v_mfma_f32_32x32x16_bf16 v[2:17], v[180:183], v[50:53], v[2:17]
	v_exp_f32_e32 v65, v65
	v_add_f32_e32 v231, v231, v62
	v_add_f32_e32 v232, v232, v63
	v_add_f32_e32 v231, v231, v64
	v_add_f32_e32 v232, v232, v65
	v_mfma_f32_32x32x16_bf16 v[18:33], v[184:187], v[50:53], v[18:33]
	v_cvt_pk_bf16_f32 v58, v58, v59
	v_cvt_pk_bf16_f32 v59, v60, v61
	v_cvt_pk_bf16_f32 v60, v62, v63
	v_cvt_pk_bf16_f32 v61, v64, v65
	v_max3_f32 v234, v66, v67, v68
	v_max3_f32 v235, v82, v83, v84
	s_waitcnt lgkmcnt(2)
	v_mfma_f32_32x32x16_bf16 v[2:17], v[188:191], v[58:61], v[2:17]
	v_max3_f32 v234, v234, v69, v70
	v_max3_f32 v235, v235, v85, v86
	v_max3_f32 v234, v234, v71, v72
	v_max3_f32 v235, v235, v87, v88
	v_max3_f32 v234, v234, v73, v74
	v_max3_f32 v235, v235, v89, v90
	v_max3_f32 v234, v234, v75, v76
	v_mfma_f32_32x32x16_bf16 v[18:33], v[192:195], v[58:61], v[18:33]
	v_max3_f32 v235, v235, v91, v92
	v_max3_f32 v234, v234, v77, v78
	v_max3_f32 v235, v235, v93, v94
	v_max3_f32 v234, v234, v79, v80
	v_max3_f32 v235, v235, v95, v96
	v_max3_f32 v234, v234, v81, v97
	v_max_f32_e32 v234, v234, v235
	v_mov_b32_e32 v235, v234
	s_nop 1
	v_permlane32_swap_b32_e32 v234, v235
	v_max_f32_e32 v233, v234, v235
	v_cmp_lt_f32_e32 vcc, 4.0, v233
	s_cbranch_vccz .Lmls_nr_p2
	s_nop 15
	v_max_f32_e32 v234, 0, v233
	v_exp_f32_e64 v235, -v234
	v_add_f32_e32 v230, v230, v234
	v_sub_f32_e32 v66, v66, v234
	v_sub_f32_e32 v67, v67, v234
	v_sub_f32_e32 v68, v68, v234
	v_sub_f32_e32 v69, v69, v234
	v_sub_f32_e32 v70, v70, v234
	v_sub_f32_e32 v71, v71, v234
	v_sub_f32_e32 v72, v72, v234
	v_sub_f32_e32 v73, v73, v234
	v_sub_f32_e32 v74, v74, v234
	v_sub_f32_e32 v75, v75, v234
	v_sub_f32_e32 v76, v76, v234
	v_sub_f32_e32 v77, v77, v234
	v_sub_f32_e32 v78, v78, v234
	v_sub_f32_e32 v79, v79, v234
	v_sub_f32_e32 v80, v80, v234
	v_sub_f32_e32 v81, v81, v234
	v_sub_f32_e32 v82, v82, v234
	v_sub_f32_e32 v83, v83, v234
	v_sub_f32_e32 v84, v84, v234
	v_sub_f32_e32 v85, v85, v234
	v_sub_f32_e32 v86, v86, v234
	v_sub_f32_e32 v87, v87, v234
	v_sub_f32_e32 v88, v88, v234
	v_sub_f32_e32 v89, v89, v234
	v_sub_f32_e32 v90, v90, v234
	v_sub_f32_e32 v91, v91, v234
	v_sub_f32_e32 v92, v92, v234
	v_sub_f32_e32 v93, v93, v234
	v_sub_f32_e32 v94, v94, v234
	v_sub_f32_e32 v95, v95, v234
	v_sub_f32_e32 v96, v96, v234
	v_sub_f32_e32 v97, v97, v234
	v_mul_f32_e32 v231, v231, v235
	v_mul_f32_e32 v232, v232, v235
	v_mul_f32_e32 v2, v2, v235
	v_mul_f32_e32 v3, v3, v235
	v_mul_f32_e32 v4, v4, v235
	v_mul_f32_e32 v5, v5, v235
	v_mul_f32_e32 v6, v6, v235
	v_mul_f32_e32 v7, v7, v235
	v_mul_f32_e32 v8, v8, v235
	v_mul_f32_e32 v9, v9, v235
	v_mul_f32_e32 v10, v10, v235
	v_mul_f32_e32 v11, v11, v235
	v_mul_f32_e32 v12, v12, v235
	v_mul_f32_e32 v13, v13, v235
	v_mul_f32_e32 v14, v14, v235
	v_mul_f32_e32 v15, v15, v235
	v_mul_f32_e32 v16, v16, v235
	v_mul_f32_e32 v17, v17, v235
	v_mul_f32_e32 v18, v18, v235
	v_mul_f32_e32 v19, v19, v235
	v_mul_f32_e32 v20, v20, v235
	v_mul_f32_e32 v21, v21, v235
	v_mul_f32_e32 v22, v22, v235
	v_mul_f32_e32 v23, v23, v235
	v_mul_f32_e32 v24, v24, v235
	v_mul_f32_e32 v25, v25, v235
	v_mul_f32_e32 v26, v26, v235
	v_mul_f32_e32 v27, v27, v235
	v_mul_f32_e32 v28, v28, v235
	v_mul_f32_e32 v29, v29, v235
	v_mul_f32_e32 v30, v30, v235
	v_mul_f32_e32 v31, v31, v235
	v_mul_f32_e32 v32, v32, v235
	v_mul_f32_e32 v33, v33, v235
	v_sub_f32_e32 v122, 0, v230
	v_mov_b32_e32 v123, v122
	v_mov_b32_e32 v124, v122
	v_mov_b32_e32 v125, v122
	v_mov_b32_e32 v126, v122
	v_mov_b32_e32 v127, v122
	v_mov_b32_e32 v128, v122
	v_mov_b32_e32 v129, v122
	v_mov_b32_e32 v130, v122
	v_mov_b32_e32 v131, v122
	v_mov_b32_e32 v132, v122
	v_mov_b32_e32 v133, v122
	v_mov_b32_e32 v134, v122
	v_mov_b32_e32 v135, v122
	v_mov_b32_e32 v136, v122
	v_mov_b32_e32 v137, v122
.Lmls_nr_p2:
	ds_read_b128 v[138:141], v220 offset:0
	ds_read_b128 v[142:145], v220 offset:6656
	ds_read_b128 v[146:149], v220 offset:32
	ds_read_b128 v[150:153], v220 offset:6688
	ds_read_b128 v[154:157], v220 offset:64
	ds_read_b128 v[158:161], v220 offset:6720
	s_waitcnt lgkmcnt(6)
	s_barrier
	s_waitcnt lgkmcnt(4)
	v_mfma_f32_32x32x16_bf16 v[34:49], v[138:141], v[98:101], v[122:137]
	ds_read_b128 v[138:141], v220 offset:96
	v_exp_f32_e32 v66, v66
	v_exp_f32_e32 v67, v67
	v_exp_f32_e32 v68, v68
	v_exp_f32_e32 v69, v69
	v_mfma_f32_32x32x16_bf16 v[50:65], v[142:145], v[98:101], v[122:137]
	ds_read_b128 v[142:145], v220 offset:6752
	v_add_f32_e32 v231, v231, v66
	v_add_f32_e32 v232, v232, v67
	v_exp_f32_e32 v70, v70
	v_exp_f32_e32 v71, v71
	s_waitcnt lgkmcnt(4)
	v_mfma_f32_32x32x16_bf16 v[34:49], v[146:149], v[102:105], v[34:49]
	ds_read_b128 v[146:149], v220 offset:128
	global_load_dwordx4 v[216:219], v229, s[10:11]
	s_add_u32 s10, s10, 0x80
	s_addc_u32 s11, s11, 0
	v_add_f32_e32 v231, v231, v68
	v_add_f32_e32 v232, v232, v69
	v_exp_f32_e32 v72, v72
	v_exp_f32_e32 v73, v73
	v_mfma_f32_32x32x16_bf16 v[50:65], v[150:153], v[102:105], v[50:65]
	ds_read_b128 v[150:153], v220 offset:6784
	v_add_f32_e32 v231, v231, v70
	v_add_f32_e32 v232, v232, v71
	v_add_f32_e32 v231, v231, v72
	v_add_f32_e32 v232, v232, v73
	v_cvt_pk_bf16_f32 v66, v66, v67
	v_cvt_pk_bf16_f32 v67, v68, v69
	s_waitcnt lgkmcnt(4)
	v_mfma_f32_32x32x16_bf16 v[34:49], v[154:157], v[106:109], v[34:49]
	ds_read_b128 v[154:157], v220 offset:160
	v_cvt_pk_bf16_f32 v68, v70, v71
	v_cvt_pk_bf16_f32 v69, v72, v73
	v_exp_f32_e32 v74, v74
	v_exp_f32_e32 v75, v75
	v_mfma_f32_32x32x16_bf16 v[50:65], v[158:161], v[106:109], v[50:65]
	ds_read_b128 v[158:161], v220 offset:6816
	v_exp_f32_e32 v76, v76
	v_exp_f32_e32 v77, v77
	v_add_f32_e32 v231, v231, v74
	v_add_f32_e32 v232, v232, v75
	s_waitcnt lgkmcnt(4)
	v_mfma_f32_32x32x16_bf16 v[34:49], v[138:141], v[110:113], v[34:49]
	ds_read_b128 v[162:165], v221 offset:27648
	v_exp_f32_e32 v78, v78
	v_exp_f32_e32 v79, v79
	v_add_f32_e32 v231, v231, v76
	v_add_f32_e32 v232, v232, v77
	v_exp_f32_e32 v80, v80
	v_mfma_f32_32x32x16_bf16 v[50:65], v[142:145], v[110:113], v[50:65]
	ds_read_b128 v[166:169], v221 offset:32256
	v_exp_f32_e32 v81, v81
	v_add_f32_e32 v231, v231, v78
	v_add_f32_e32 v232, v232, v79
	v_add_f32_e32 v231, v231, v80
	s_waitcnt lgkmcnt(4)
	v_mfma_f32_32x32x16_bf16 v[34:49], v[146:149], v[114:117], v[34:49]
	ds_read_b128 v[170:173], v221 offset:27680
	v_add_f32_e32 v232, v232, v81
	v_cvt_pk_bf16_f32 v74, v74, v75
	v_cvt_pk_bf16_f32 v75, v76, v77
	v_cvt_pk_bf16_f32 v76, v78, v79
	v_cvt_pk_bf16_f32 v77, v80, v81
	v_exp_f32_e32 v82, v82
	v_mfma_f32_32x32x16_bf16 v[50:65], v[150:153], v[114:117], v[50:65]
	ds_read_b128 v[174:177], v221 offset:32288
	v_exp_f32_e32 v83, v83
	v_exp_f32_e32 v84, v84
	v_exp_f32_e32 v85, v85
	s_waitcnt lgkmcnt(4)
	v_mfma_f32_32x32x16_bf16 v[34:49], v[154:157], v[118:121], v[34:49]
	ds_read_b128 v[180:183], v221 offset:27712
	v_add_f32_e32 v231, v231, v82
	v_add_f32_e32 v232, v232, v83
	v_exp_f32_e32 v86, v86
	v_exp_f32_e32 v87, v87
	v_mfma_f32_32x32x16_bf16 v[50:65], v[158:161], v[118:121], v[50:65]
	ds_read_b128 v[184:187], v221 offset:32320
	v_add_f32_e32 v231, v231, v84
	v_add_f32_e32 v232, v232, v85
	v_exp_f32_e32 v88, v88
	v_exp_f32_e32 v89, v89
	s_waitcnt lgkmcnt(4)
	v_mfma_f32_32x32x16_bf16 v[2:17], v[162:165], v[66:69], v[2:17]
	ds_read_b128 v[188:191], v221 offset:27744
	v_add_f32_e32 v231, v231, v86
	v_add_f32_e32 v232, v232, v87
	v_add_f32_e32 v231, v231, v88
	v_add_f32_e32 v232, v232, v89
	v_cvt_pk_bf16_f32 v82, v82, v83
	v_cvt_pk_bf16_f32 v83, v84, v85
	v_cvt_pk_bf16_f32 v84, v86, v87
	v_mfma_f32_32x32x16_bf16 v[18:33], v[166:169], v[66:69], v[18:33]
	ds_read_b128 v[192:195], v221 offset:32352
	v_cvt_pk_bf16_f32 v85, v88, v89
	v_exp_f32_e32 v90, v90
	v_exp_f32_e32 v91, v91
	v_exp_f32_e32 v92, v92
	s_waitcnt lgkmcnt(4)
	v_mfma_f32_32x32x16_bf16 v[2:17], v[170:173], v[74:77], v[2:17]
	v_exp_f32_e32 v93, v93
	v_add_f32_e32 v231, v231, v90
	v_add_f32_e32 v232, v232, v91
	v_exp_f32_e32 v94, v94
	v_mfma_f32_32x32x16_bf16 v[18:33], v[174:177], v[74:77], v[18:33]
	s_waitcnt vmcnt(1)
	ds_write_b128 v222, v[200:203] offset:26624
	ds_write_b128 v223, v[204:207] offset:26624
	ds_write_b128 v224, v[208:211] offset:26624
	ds_write_b64 v225, v[212:213] offset:9216
	ds_write_b64 v225, v[214:215] offset:9232
	v_exp_f32_e32 v95, v95
	v_add_f32_e32 v231, v231, v92
	v_add_f32_e32 v232, v232, v93
	v_exp_f32_e32 v96, v96
	s_waitcnt lgkmcnt(7)
	v_mfma_f32_32x32x16_bf16 v[2:17], v[180:183], v[82:85], v[2:17]
	v_exp_f32_e32 v97, v97
	v_add_f32_e32 v231, v231, v94
	v_add_f32_e32 v232, v232, v95
	v_add_f32_e32 v231, v231, v96
	v_add_f32_e32 v232, v232, v97
	v_mfma_f32_32x32x16_bf16 v[18:33], v[184:187], v[82:85], v[18:33]
	v_cvt_pk_bf16_f32 v90, v90, v91
	v_cvt_pk_bf16_f32 v91, v92, v93
	v_cvt_pk_bf16_f32 v92, v94, v95
	v_cvt_pk_bf16_f32 v93, v96, v97
	v_max3_f32 v234, v34, v35, v36
	v_max3_f32 v235, v50, v51, v52
	s_waitcnt lgkmcnt(5)
	v_mfma_f32_32x32x16_bf16 v[2:17], v[188:191], v[90:93], v[2:17]
	v_max3_f32 v234, v234, v37, v38
	v_max3_f32 v235, v235, v53, v54
	v_max3_f32 v234, v234, v39, v40
	v_max3_f32 v235, v235, v55, v56
	v_max3_f32 v234, v234, v41, v42
	v_max3_f32 v235, v235, v57, v58
	v_max3_f32 v234, v234, v43, v44
	v_mfma_f32_32x32x16_bf16 v[18:33], v[192:195], v[90:93], v[18:33]
	v_max3_f32 v235, v235, v59, v60
	v_max3_f32 v234, v234, v45, v46
	v_max3_f32 v235, v235, v61, v62
	v_max3_f32 v234, v234, v47, v48
	v_max3_f32 v235, v235, v63, v64
	v_max3_f32 v234, v234, v49, v65
	v_max_f32_e32 v234, v234, v235
	v_mov_b32_e32 v235, v234
	s_nop 1
	v_permlane32_swap_b32_e32 v234, v235
	v_max_f32_e32 v233, v234, v235
	v_cmp_lt_f32_e32 vcc, 4.0, v233
	s_cbranch_vccz .Lmls_nr_p3
	s_nop 15
	v_max_f32_e32 v234, 0, v233
	v_exp_f32_e64 v235, -v234
	v_add_f32_e32 v230, v230, v234
	v_sub_f32_e32 v34, v34, v234
	v_sub_f32_e32 v35, v35, v234
	v_sub_f32_e32 v36, v36, v234
	v_sub_f32_e32 v37, v37, v234
	v_sub_f32_e32 v38, v38, v234
	v_sub_f32_e32 v39, v39, v234
	v_sub_f32_e32 v40, v40, v234
	v_sub_f32_e32 v41, v41, v234
	v_sub_f32_e32 v42, v42, v234
	v_sub_f32_e32 v43, v43, v234
	v_sub_f32_e32 v44, v44, v234
	v_sub_f32_e32 v45, v45, v234
	v_sub_f32_e32 v46, v46, v234
	v_sub_f32_e32 v47, v47, v234
	v_sub_f32_e32 v48, v48, v234
	v_sub_f32_e32 v49, v49, v234
	v_sub_f32_e32 v50, v50, v234
	v_sub_f32_e32 v51, v51, v234
	v_sub_f32_e32 v52, v52, v234
	v_sub_f32_e32 v53, v53, v234
	v_sub_f32_e32 v54, v54, v234
	v_sub_f32_e32 v55, v55, v234
	v_sub_f32_e32 v56, v56, v234
	v_sub_f32_e32 v57, v57, v234
	v_sub_f32_e32 v58, v58, v234
	v_sub_f32_e32 v59, v59, v234
	v_sub_f32_e32 v60, v60, v234
	v_sub_f32_e32 v61, v61, v234
	v_sub_f32_e32 v62, v62, v234
	v_sub_f32_e32 v63, v63, v234
	v_sub_f32_e32 v64, v64, v234
	v_sub_f32_e32 v65, v65, v234
	v_mul_f32_e32 v231, v231, v235
	v_mul_f32_e32 v232, v232, v235
	v_mul_f32_e32 v2, v2, v235
	v_mul_f32_e32 v3, v3, v235
	v_mul_f32_e32 v4, v4, v235
	v_mul_f32_e32 v5, v5, v235
	v_mul_f32_e32 v6, v6, v235
	v_mul_f32_e32 v7, v7, v235
	v_mul_f32_e32 v8, v8, v235
	v_mul_f32_e32 v9, v9, v235
	v_mul_f32_e32 v10, v10, v235
	v_mul_f32_e32 v11, v11, v235
	v_mul_f32_e32 v12, v12, v235
	v_mul_f32_e32 v13, v13, v235
	v_mul_f32_e32 v14, v14, v235
	v_mul_f32_e32 v15, v15, v235
	v_mul_f32_e32 v16, v16, v235
	v_mul_f32_e32 v17, v17, v235
	v_mul_f32_e32 v18, v18, v235
	v_mul_f32_e32 v19, v19, v235
	v_mul_f32_e32 v20, v20, v235
	v_mul_f32_e32 v21, v21, v235
	v_mul_f32_e32 v22, v22, v235
	v_mul_f32_e32 v23, v23, v235
	v_mul_f32_e32 v24, v24, v235
	v_mul_f32_e32 v25, v25, v235
	v_mul_f32_e32 v26, v26, v235
	v_mul_f32_e32 v27, v27, v235
	v_mul_f32_e32 v28, v28, v235
	v_mul_f32_e32 v29, v29, v235
	v_mul_f32_e32 v30, v30, v235
	v_mul_f32_e32 v31, v31, v235
	v_mul_f32_e32 v32, v32, v235
	v_mul_f32_e32 v33, v33, v235
	v_sub_f32_e32 v122, 0, v230
	v_mov_b32_e32 v123, v122
	v_mov_b32_e32 v124, v122
	v_mov_b32_e32 v125, v122
	v_mov_b32_e32 v126, v122
	v_mov_b32_e32 v127, v122
	v_mov_b32_e32 v128, v122
	v_mov_b32_e32 v129, v122
	v_mov_b32_e32 v130, v122
	v_mov_b32_e32 v131, v122
	v_mov_b32_e32 v132, v122
	v_mov_b32_e32 v133, v122
	v_mov_b32_e32 v134, v122
	v_mov_b32_e32 v135, v122
	v_mov_b32_e32 v136, v122
	v_mov_b32_e32 v137, v122
.Lmls_nr_p3:
	ds_read_b128 v[138:141], v220 offset:13312
	ds_read_b128 v[142:145], v220 offset:19968
	ds_read_b128 v[146:149], v220 offset:13344
	ds_read_b128 v[150:153], v220 offset:20000
	ds_read_b128 v[154:157], v220 offset:13376
	ds_read_b128 v[158:161], v220 offset:20032
	s_waitcnt lgkmcnt(6)
	s_barrier
	s_add_i32 s16, s16, -1
	s_cmp_lg_u32 s16, 0
	s_cbranch_scc1 .Lmls_loop
	s_waitcnt lgkmcnt(4)
	v_mfma_f32_32x32x16_bf16 v[66:81], v[138:141], v[98:101], v[122:137]
	ds_read_b128 v[138:141], v220 offset:13408
	v_exp_f32_e32 v34, v34
	v_exp_f32_e32 v35, v35
	v_exp_f32_e32 v36, v36
	v_exp_f32_e32 v37, v37
	v_mfma_f32_32x32x16_bf16 v[82:97], v[142:145], v[98:101], v[122:137]
	ds_read_b128 v[142:145], v220 offset:20064
	v_add_f32_e32 v231, v231, v34
	v_add_f32_e32 v232, v232, v35
	v_exp_f32_e32 v38, v38
	v_exp_f32_e32 v39, v39
	s_waitcnt lgkmcnt(4)
	v_mfma_f32_32x32x16_bf16 v[66:81], v[146:149], v[102:105], v[66:81]
	ds_read_b128 v[146:149], v220 offset:13440
	global_load_dwordx4 v[212:215], v229, s[10:11]
	s_add_u32 s10, s10, 0x80
	s_addc_u32 s11, s11, 0
	v_add_f32_e32 v231, v231, v36
	v_add_f32_e32 v232, v232, v37
	v_exp_f32_e32 v40, v40
	v_exp_f32_e32 v41, v41
	v_mfma_f32_32x32x16_bf16 v[82:97], v[150:153], v[102:105], v[82:97]
	ds_read_b128 v[150:153], v220 offset:20096
	v_add_f32_e32 v231, v231, v38
	v_add_f32_e32 v232, v232, v39
	v_add_f32_e32 v231, v231, v40
	v_add_f32_e32 v232, v232, v41
	v_cvt_pk_bf16_f32 v34, v34, v35
	v_cvt_pk_bf16_f32 v35, v36, v37
	s_waitcnt lgkmcnt(4)
	v_mfma_f32_32x32x16_bf16 v[66:81], v[154:157], v[106:109], v[66:81]
	ds_read_b128 v[154:157], v220 offset:13472
	v_cvt_pk_bf16_f32 v36, v38, v39
	v_cvt_pk_bf16_f32 v37, v40, v41
	v_exp_f32_e32 v42, v42
	v_exp_f32_e32 v43, v43
	v_mfma_f32_32x32x16_bf16 v[82:97], v[158:161], v[106:109], v[82:97]
	ds_read_b128 v[158:161], v220 offset:20128
	v_exp_f32_e32 v44, v44
	v_exp_f32_e32 v45, v45
	v_add_f32_e32 v231, v231, v42
	v_add_f32_e32 v232, v232, v43
	s_waitcnt lgkmcnt(4)
	v_mfma_f32_32x32x16_bf16 v[66:81], v[138:141], v[110:113], v[66:81]
	ds_read_b128 v[162:165], v221 offset:0
	v_exp_f32_e32 v46, v46
	v_exp_f32_e32 v47, v47
	v_add_f32_e32 v231, v231, v44
	v_add_f32_e32 v232, v232, v45
	v_exp_f32_e32 v48, v48
	v_mfma_f32_32x32x16_bf16 v[82:97], v[142:145], v[110:113], v[82:97]
	ds_read_b128 v[166:169], v221 offset:4608
	v_exp_f32_e32 v49, v49
	v_add_f32_e32 v231, v231, v46
	v_add_f32_e32 v232, v232, v47
	v_add_f32_e32 v231, v231, v48
	s_waitcnt lgkmcnt(4)
	v_mfma_f32_32x32x16_bf16 v[66:81], v[146:149], v[114:117], v[66:81]
	ds_read_b128 v[170:173], v221 offset:32
	v_add_f32_e32 v232, v232, v49
	v_cvt_pk_bf16_f32 v42, v42, v43
	v_cvt_pk_bf16_f32 v43, v44, v45
	v_cvt_pk_bf16_f32 v44, v46, v47
	v_cvt_pk_bf16_f32 v45, v48, v49
	v_exp_f32_e32 v50, v50
	v_mfma_f32_32x32x16_bf16 v[82:97], v[150:153], v[114:117], v[82:97]
	ds_read_b128 v[174:177], v221 offset:4640
	v_exp_f32_e32 v51, v51
	v_exp_f32_e32 v52, v52
	v_exp_f32_e32 v53, v53
	s_waitcnt lgkmcnt(4)
	v_mfma_f32_32x32x16_bf16 v[66:81], v[154:157], v[118:121], v[66:81]
	ds_read_b128 v[180:183], v221 offset:64
	v_add_f32_e32 v231, v231, v50
	v_add_f32_e32 v232, v232, v51
	v_exp_f32_e32 v54, v54
	v_exp_f32_e32 v55, v55
	v_mfma_f32_32x32x16_bf16 v[82:97], v[158:161], v[118:121], v[82:97]
	ds_read_b128 v[184:187], v221 offset:4672
	v_add_f32_e32 v231, v231, v52
	v_add_f32_e32 v232, v232, v53
	v_exp_f32_e32 v56, v56
	v_exp_f32_e32 v57, v57
	s_waitcnt lgkmcnt(4)
	v_mfma_f32_32x32x16_bf16 v[2:17], v[162:165], v[34:37], v[2:17]
	ds_read_b128 v[188:191], v221 offset:96
	v_add_f32_e32 v231, v231, v54
	v_add_f32_e32 v232, v232, v55
	v_add_f32_e32 v231, v231, v56
	v_add_f32_e32 v232, v232, v57
	v_cvt_pk_bf16_f32 v50, v50, v51
	v_cvt_pk_bf16_f32 v51, v52, v53
	v_cvt_pk_bf16_f32 v52, v54, v55
	v_mfma_f32_32x32x16_bf16 v[18:33], v[166:169], v[34:37], v[18:33]
	ds_read_b128 v[192:195], v221 offset:4704
	v_cvt_pk_bf16_f32 v53, v56, v57
	v_exp_f32_e32 v58, v58
	v_exp_f32_e32 v59, v59
	v_exp_f32_e32 v60, v60
	s_waitcnt lgkmcnt(4)
	v_mfma_f32_32x32x16_bf16 v[2:17], v[170:173], v[42:45], v[2:17]
	v_exp_f32_e32 v61, v61
	v_add_f32_e32 v231, v231, v58
	v_add_f32_e32 v232, v232, v59
	v_exp_f32_e32 v62, v62
	v_mfma_f32_32x32x16_bf16 v[18:33], v[174:177], v[42:45], v[18:33]
	s_waitcnt vmcnt(1)
	ds_write_b64 v225, v[216:217] offset:18432
	ds_write_b64 v225, v[218:219] offset:18448
	v_exp_f32_e32 v63, v63
	v_add_f32_e32 v231, v231, v60
	v_add_f32_e32 v232, v232, v61
	v_exp_f32_e32 v64, v64
	s_waitcnt lgkmcnt(4)
	v_mfma_f32_32x32x16_bf16 v[2:17], v[180:183], v[50:53], v[2:17]
	v_exp_f32_e32 v65, v65
	v_add_f32_e32 v231, v231, v62
	v_add_f32_e32 v232, v232, v63
	v_add_f32_e32 v231, v231, v64
	v_add_f32_e32 v232, v232, v65
	v_mfma_f32_32x32x16_bf16 v[18:33], v[184:187], v[50:53], v[18:33]
	v_cvt_pk_bf16_f32 v58, v58, v59
	v_cvt_pk_bf16_f32 v59, v60, v61
	v_cvt_pk_bf16_f32 v60, v62, v63
	v_cvt_pk_bf16_f32 v61, v64, v65
	v_max3_f32 v234, v66, v67, v68
	v_max3_f32 v235, v82, v83, v84
	s_waitcnt lgkmcnt(2)
	v_mfma_f32_32x32x16_bf16 v[2:17], v[188:191], v[58:61], v[2:17]
	v_max3_f32 v234, v234, v69, v70
	v_max3_f32 v235, v235, v85, v86
	v_max3_f32 v234, v234, v71, v72
	v_max3_f32 v235, v235, v87, v88
	v_max3_f32 v234, v234, v73, v74
	v_max3_f32 v235, v235, v89, v90
	v_max3_f32 v234, v234, v75, v76
	v_mfma_f32_32x32x16_bf16 v[18:33], v[192:195], v[58:61], v[18:33]
	v_max3_f32 v235, v235, v91, v92
	v_max3_f32 v234, v234, v77, v78
	v_max3_f32 v235, v235, v93, v94
	v_max3_f32 v234, v234, v79, v80
	v_max3_f32 v235, v235, v95, v96
	v_max3_f32 v234, v234, v81, v97
	v_max_f32_e32 v234, v234, v235
	v_mov_b32_e32 v235, v234
	s_nop 1
	v_permlane32_swap_b32_e32 v234, v235
	v_max_f32_e32 v233, v234, v235
	v_cmp_lt_f32_e32 vcc, 4.0, v233
	s_cbranch_vccz .Lmls_nr_t0
	s_nop 15
	v_max_f32_e32 v234, 0, v233
	v_exp_f32_e64 v235, -v234
	v_add_f32_e32 v230, v230, v234
	v_sub_f32_e32 v66, v66, v234
	v_sub_f32_e32 v67, v67, v234
	v_sub_f32_e32 v68, v68, v234
	v_sub_f32_e32 v69, v69, v234
	v_sub_f32_e32 v70, v70, v234
	v_sub_f32_e32 v71, v71, v234
	v_sub_f32_e32 v72, v72, v234
	v_sub_f32_e32 v73, v73, v234
	v_sub_f32_e32 v74, v74, v234
	v_sub_f32_e32 v75, v75, v234
	v_sub_f32_e32 v76, v76, v234
	v_sub_f32_e32 v77, v77, v234
	v_sub_f32_e32 v78, v78, v234
	v_sub_f32_e32 v79, v79, v234
	v_sub_f32_e32 v80, v80, v234
	v_sub_f32_e32 v81, v81, v234
	v_sub_f32_e32 v82, v82, v234
	v_sub_f32_e32 v83, v83, v234
	v_sub_f32_e32 v84, v84, v234
	v_sub_f32_e32 v85, v85, v234
	v_sub_f32_e32 v86, v86, v234
	v_sub_f32_e32 v87, v87, v234
	v_sub_f32_e32 v88, v88, v234
	v_sub_f32_e32 v89, v89, v234
	v_sub_f32_e32 v90, v90, v234
	v_sub_f32_e32 v91, v91, v234
	v_sub_f32_e32 v92, v92, v234
	v_sub_f32_e32 v93, v93, v234
	v_sub_f32_e32 v94, v94, v234
	v_sub_f32_e32 v95, v95, v234
	v_sub_f32_e32 v96, v96, v234
	v_sub_f32_e32 v97, v97, v234
	v_mul_f32_e32 v231, v231, v235
	v_mul_f32_e32 v232, v232, v235
	v_mul_f32_e32 v2, v2, v235
	v_mul_f32_e32 v3, v3, v235
	v_mul_f32_e32 v4, v4, v235
	v_mul_f32_e32 v5, v5, v235
	v_mul_f32_e32 v6, v6, v235
	v_mul_f32_e32 v7, v7, v235
	v_mul_f32_e32 v8, v8, v235
	v_mul_f32_e32 v9, v9, v235
	v_mul_f32_e32 v10, v10, v235
	v_mul_f32_e32 v11, v11, v235
	v_mul_f32_e32 v12, v12, v235
	v_mul_f32_e32 v13, v13, v235
	v_mul_f32_e32 v14, v14, v235
	v_mul_f32_e32 v15, v15, v235
	v_mul_f32_e32 v16, v16, v235
	v_mul_f32_e32 v17, v17, v235
	v_mul_f32_e32 v18, v18, v235
	v_mul_f32_e32 v19, v19, v235
	v_mul_f32_e32 v20, v20, v235
	v_mul_f32_e32 v21, v21, v235
	v_mul_f32_e32 v22, v22, v235
	v_mul_f32_e32 v23, v23, v235
	v_mul_f32_e32 v24, v24, v235
	v_mul_f32_e32 v25, v25, v235
	v_mul_f32_e32 v26, v26, v235
	v_mul_f32_e32 v27, v27, v235
	v_mul_f32_e32 v28, v28, v235
	v_mul_f32_e32 v29, v29, v235
	v_mul_f32_e32 v30, v30, v235
	v_mul_f32_e32 v31, v31, v235
	v_mul_f32_e32 v32, v32, v235
	v_mul_f32_e32 v33, v33, v235
	v_sub_f32_e32 v122, 0, v230
	v_mov_b32_e32 v123, v122
	v_mov_b32_e32 v124, v122
	v_mov_b32_e32 v125, v122
	v_mov_b32_e32 v126, v122
	v_mov_b32_e32 v127, v122
	v_mov_b32_e32 v128, v122
	v_mov_b32_e32 v129, v122
	v_mov_b32_e32 v130, v122
	v_mov_b32_e32 v131, v122
	v_mov_b32_e32 v132, v122
	v_mov_b32_e32 v133, v122
	v_mov_b32_e32 v134, v122
	v_mov_b32_e32 v135, v122
	v_mov_b32_e32 v136, v122
	v_mov_b32_e32 v137, v122
.Lmls_nr_t0:
	ds_read_b128 v[138:141], v220 offset:26624
	ds_read_b128 v[142:145], v220 offset:33280
	ds_read_b128 v[146:149], v220 offset:26656
	ds_read_b128 v[150:153], v220 offset:33312
	ds_read_b128 v[154:157], v220 offset:26688
	ds_read_b128 v[158:161], v220 offset:33344
	s_waitcnt lgkmcnt(6)
	s_barrier
	s_waitcnt lgkmcnt(4)
	v_mfma_f32_32x32x16_bf16 v[34:49], v[138:141], v[98:101], v[122:137]
	ds_read_b128 v[138:141], v220 offset:26720
	v_exp_f32_e32 v66, v66
	v_exp_f32_e32 v67, v67
	v_exp_f32_e32 v68, v68
	v_exp_f32_e32 v69, v69
	v_mfma_f32_32x32x16_bf16 v[50:65], v[142:145], v[98:101], v[122:137]
	ds_read_b128 v[142:145], v220 offset:33376
	v_add_f32_e32 v231, v231, v66
	v_add_f32_e32 v232, v232, v67
	v_exp_f32_e32 v70, v70
	v_exp_f32_e32 v71, v71
	s_waitcnt lgkmcnt(4)
	v_mfma_f32_32x32x16_bf16 v[34:49], v[146:149], v[102:105], v[34:49]
	ds_read_b128 v[146:149], v220 offset:26752
	v_add_f32_e32 v231, v231, v68
	v_add_f32_e32 v232, v232, v69
	v_exp_f32_e32 v72, v72
	v_exp_f32_e32 v73, v73
	v_mfma_f32_32x32x16_bf16 v[50:65], v[150:153], v[102:105], v[50:65]
	ds_read_b128 v[150:153], v220 offset:33408
	v_add_f32_e32 v231, v231, v70
	v_add_f32_e32 v232, v232, v71
	v_add_f32_e32 v231, v231, v72
	v_add_f32_e32 v232, v232, v73
	v_cvt_pk_bf16_f32 v66, v66, v67
	v_cvt_pk_bf16_f32 v67, v68, v69
	s_waitcnt lgkmcnt(4)
	v_mfma_f32_32x32x16_bf16 v[34:49], v[154:157], v[106:109], v[34:49]
	ds_read_b128 v[154:157], v220 offset:26784
	v_cvt_pk_bf16_f32 v68, v70, v71
	v_cvt_pk_bf16_f32 v69, v72, v73
	v_exp_f32_e32 v74, v74
	v_exp_f32_e32 v75, v75
	v_mfma_f32_32x32x16_bf16 v[50:65], v[158:161], v[106:109], v[50:65]
	ds_read_b128 v[158:161], v220 offset:33440
	v_exp_f32_e32 v76, v76
	v_exp_f32_e32 v77, v77
	v_add_f32_e32 v231, v231, v74
	v_add_f32_e32 v232, v232, v75
	s_waitcnt lgkmcnt(4)
	v_mfma_f32_32x32x16_bf16 v[34:49], v[138:141], v[110:113], v[34:49]
	ds_read_b128 v[162:165], v221 offset:9216
	v_exp_f32_e32 v78, v78
	v_exp_f32_e32 v79, v79
	v_add_f32_e32 v231, v231, v76
	v_add_f32_e32 v232, v232, v77
	v_exp_f32_e32 v80, v80
	v_mfma_f32_32x32x16_bf16 v[50:65], v[142:145], v[110:113], v[50:65]
	ds_read_b128 v[166:169], v221 offset:13824
	v_exp_f32_e32 v81, v81
	v_add_f32_e32 v231, v231, v78
	v_add_f32_e32 v232, v232, v79
	v_add_f32_e32 v231, v231, v80
	s_waitcnt lgkmcnt(4)
	v_mfma_f32_32x32x16_bf16 v[34:49], v[146:149], v[114:117], v[34:49]
	ds_read_b128 v[170:173], v221 offset:9248
	v_add_f32_e32 v232, v232, v81
	v_cvt_pk_bf16_f32 v74, v74, v75
	v_cvt_pk_bf16_f32 v75, v76, v77
	v_cvt_pk_bf16_f32 v76, v78, v79
	v_cvt_pk_bf16_f32 v77, v80, v81
	v_exp_f32_e32 v82, v82
	v_mfma_f32_32x32x16_bf16 v[50:65], v[150:153], v[114:117], v[50:65]
	ds_read_b128 v[174:177], v221 offset:13856
	v_exp_f32_e32 v83, v83
	v_exp_f32_e32 v84, v84
	v_exp_f32_e32 v85, v85
	s_waitcnt lgkmcnt(4)
	v_mfma_f32_32x32x16_bf16 v[34:49], v[154:157], v[118:121], v[34:49]
	ds_read_b128 v[180:183], v221 offset:9280
	v_add_f32_e32 v231, v231, v82
	v_add_f32_e32 v232, v232, v83
	v_exp_f32_e32 v86, v86
	v_exp_f32_e32 v87, v87
	v_mfma_f32_32x32x16_bf16 v[50:65], v[158:161], v[118:121], v[50:65]
	ds_read_b128 v[184:187], v221 offset:13888
	v_add_f32_e32 v231, v231, v84
	v_add_f32_e32 v232, v232, v85
	v_exp_f32_e32 v88, v88
	v_exp_f32_e32 v89, v89
	s_waitcnt lgkmcnt(4)
	v_mfma_f32_32x32x16_bf16 v[2:17], v[162:165], v[66:69], v[2:17]
	ds_read_b128 v[188:191], v221 offset:9312
	v_add_f32_e32 v231, v231, v86
	v_add_f32_e32 v232, v232, v87
	v_add_f32_e32 v231, v231, v88
	v_add_f32_e32 v232, v232, v89
	v_cvt_pk_bf16_f32 v82, v82, v83
	v_cvt_pk_bf16_f32 v83, v84, v85
	v_cvt_pk_bf16_f32 v84, v86, v87
	v_mfma_f32_32x32x16_bf16 v[18:33], v[166:169], v[66:69], v[18:33]
	ds_read_b128 v[192:195], v221 offset:13920
	v_cvt_pk_bf16_f32 v85, v88, v89
	v_exp_f32_e32 v90, v90
	v_exp_f32_e32 v91, v91
	v_exp_f32_e32 v92, v92
	s_waitcnt lgkmcnt(4)
	v_mfma_f32_32x32x16_bf16 v[2:17], v[170:173], v[74:77], v[2:17]
	v_exp_f32_e32 v93, v93
	v_add_f32_e32 v231, v231, v90
	v_add_f32_e32 v232, v232, v91
	v_exp_f32_e32 v94, v94
	v_mfma_f32_32x32x16_bf16 v[18:33], v[174:177], v[74:77], v[18:33]
	s_waitcnt vmcnt(0)
	ds_write_b64 v225, v[212:213] offset:27648
	ds_write_b64 v225, v[214:215] offset:27664
	v_exp_f32_e32 v95, v95
	v_add_f32_e32 v231, v231, v92
	v_add_f32_e32 v232, v232, v93
	v_exp_f32_e32 v96, v96
	s_waitcnt lgkmcnt(4)
	v_mfma_f32_32x32x16_bf16 v[2:17], v[180:183], v[82:85], v[2:17]
	v_exp_f32_e32 v97, v97
	v_add_f32_e32 v231, v231, v94
	v_add_f32_e32 v232, v232, v95
	v_add_f32_e32 v231, v231, v96
	v_add_f32_e32 v232, v232, v97
	v_mfma_f32_32x32x16_bf16 v[18:33], v[184:187], v[82:85], v[18:33]
	v_cvt_pk_bf16_f32 v90, v90, v91
	v_cvt_pk_bf16_f32 v91, v92, v93
	v_cvt_pk_bf16_f32 v92, v94, v95
	v_cvt_pk_bf16_f32 v93, v96, v97
	v_max3_f32 v234, v34, v35, v36
	v_max3_f32 v235, v50, v51, v52
	s_waitcnt lgkmcnt(2)
	v_mfma_f32_32x32x16_bf16 v[2:17], v[188:191], v[90:93], v[2:17]
	v_max3_f32 v234, v234, v37, v38
	v_max3_f32 v235, v235, v53, v54
	v_max3_f32 v234, v234, v39, v40
	v_max3_f32 v235, v235, v55, v56
	v_max3_f32 v234, v234, v41, v42
	v_max3_f32 v235, v235, v57, v58
	v_max3_f32 v234, v234, v43, v44
	v_mfma_f32_32x32x16_bf16 v[18:33], v[192:195], v[90:93], v[18:33]
	v_max3_f32 v235, v235, v59, v60
	v_max3_f32 v234, v234, v45, v46
	v_max3_f32 v235, v235, v61, v62
	v_max3_f32 v234, v234, v47, v48
	v_max3_f32 v235, v235, v63, v64
	v_max3_f32 v234, v234, v49, v65
	v_max_f32_e32 v234, v234, v235
	v_mov_b32_e32 v235, v234
	s_nop 1
	v_permlane32_swap_b32_e32 v234, v235
	v_max_f32_e32 v233, v234, v235
	v_cmp_lt_f32_e32 vcc, 4.0, v233
	s_cbranch_vccz .Lmls_nr_t1
	s_nop 15
	v_max_f32_e32 v234, 0, v233
	v_exp_f32_e64 v235, -v234
	v_add_f32_e32 v230, v230, v234
	v_sub_f32_e32 v34, v34, v234
	v_sub_f32_e32 v35, v35, v234
	v_sub_f32_e32 v36, v36, v234
	v_sub_f32_e32 v37, v37, v234
	v_sub_f32_e32 v38, v38, v234
	v_sub_f32_e32 v39, v39, v234
	v_sub_f32_e32 v40, v40, v234
	v_sub_f32_e32 v41, v41, v234
	v_sub_f32_e32 v42, v42, v234
	v_sub_f32_e32 v43, v43, v234
	v_sub_f32_e32 v44, v44, v234
	v_sub_f32_e32 v45, v45, v234
	v_sub_f32_e32 v46, v46, v234
	v_sub_f32_e32 v47, v47, v234
	v_sub_f32_e32 v48, v48, v234
	v_sub_f32_e32 v49, v49, v234
	v_sub_f32_e32 v50, v50, v234
	v_sub_f32_e32 v51, v51, v234
	v_sub_f32_e32 v52, v52, v234
	v_sub_f32_e32 v53, v53, v234
	v_sub_f32_e32 v54, v54, v234
	v_sub_f32_e32 v55, v55, v234
	v_sub_f32_e32 v56, v56, v234
	v_sub_f32_e32 v57, v57, v234
	v_sub_f32_e32 v58, v58, v234
	v_sub_f32_e32 v59, v59, v234
	v_sub_f32_e32 v60, v60, v234
	v_sub_f32_e32 v61, v61, v234
	v_sub_f32_e32 v62, v62, v234
	v_sub_f32_e32 v63, v63, v234
	v_sub_f32_e32 v64, v64, v234
	v_sub_f32_e32 v65, v65, v234
	v_mul_f32_e32 v231, v231, v235
	v_mul_f32_e32 v232, v232, v235
	v_mul_f32_e32 v2, v2, v235
	v_mul_f32_e32 v3, v3, v235
	v_mul_f32_e32 v4, v4, v235
	v_mul_f32_e32 v5, v5, v235
	v_mul_f32_e32 v6, v6, v235
	v_mul_f32_e32 v7, v7, v235
	v_mul_f32_e32 v8, v8, v235
	v_mul_f32_e32 v9, v9, v235
	v_mul_f32_e32 v10, v10, v235
	v_mul_f32_e32 v11, v11, v235
	v_mul_f32_e32 v12, v12, v235
	v_mul_f32_e32 v13, v13, v235
	v_mul_f32_e32 v14, v14, v235
	v_mul_f32_e32 v15, v15, v235
	v_mul_f32_e32 v16, v16, v235
	v_mul_f32_e32 v17, v17, v235
	v_mul_f32_e32 v18, v18, v235
	v_mul_f32_e32 v19, v19, v235
	v_mul_f32_e32 v20, v20, v235
	v_mul_f32_e32 v21, v21, v235
	v_mul_f32_e32 v22, v22, v235
	v_mul_f32_e32 v23, v23, v235
	v_mul_f32_e32 v24, v24, v235
	v_mul_f32_e32 v25, v25, v235
	v_mul_f32_e32 v26, v26, v235
	v_mul_f32_e32 v27, v27, v235
	v_mul_f32_e32 v28, v28, v235
	v_mul_f32_e32 v29, v29, v235
	v_mul_f32_e32 v30, v30, v235
	v_mul_f32_e32 v31, v31, v235
	v_mul_f32_e32 v32, v32, v235
	v_mul_f32_e32 v33, v33, v235
	v_sub_f32_e32 v122, 0, v230
	v_mov_b32_e32 v123, v122
	v_mov_b32_e32 v124, v122
	v_mov_b32_e32 v125, v122
	v_mov_b32_e32 v126, v122
	v_mov_b32_e32 v127, v122
	v_mov_b32_e32 v128, v122
	v_mov_b32_e32 v129, v122
	v_mov_b32_e32 v130, v122
	v_mov_b32_e32 v131, v122
	v_mov_b32_e32 v132, v122
	v_mov_b32_e32 v133, v122
	v_mov_b32_e32 v134, v122
	v_mov_b32_e32 v135, v122
	v_mov_b32_e32 v136, v122
	v_mov_b32_e32 v137, v122
.Lmls_nr_t1:
	ds_read_b128 v[138:141], v220 offset:39936
	ds_read_b128 v[142:145], v220 offset:46592
	ds_read_b128 v[146:149], v220 offset:39968
	ds_read_b128 v[150:153], v220 offset:46624
	ds_read_b128 v[154:157], v220 offset:40000
	ds_read_b128 v[158:161], v220 offset:46656
	s_waitcnt lgkmcnt(6)
	s_barrier
	global_load_dwordx2 v[200:201], v236, s[14:15] offset:0
	global_load_dwordx2 v[202:203], v236, s[14:15] offset:16
	global_load_dwordx2 v[204:205], v236, s[14:15] offset:32
	global_load_dwordx2 v[206:207], v236, s[14:15] offset:48
	global_load_dwordx2 v[208:209], v236, s[14:15] offset:64
	global_load_dwordx2 v[210:211], v236, s[14:15] offset:80
	global_load_dwordx2 v[212:213], v236, s[14:15] offset:96
	global_load_dwordx2 v[214:215], v236, s[14:15] offset:112
	s_waitcnt lgkmcnt(4)
	v_mfma_f32_32x32x16_bf16 v[66:81], v[138:141], v[98:101], v[122:137]
	ds_read_b128 v[138:141], v220 offset:40032
	v_exp_f32_e32 v34, v34
	v_exp_f32_e32 v35, v35
	v_exp_f32_e32 v36, v36
	v_exp_f32_e32 v37, v37
	v_mfma_f32_32x32x16_bf16 v[82:97], v[142:145], v[98:101], v[122:137]
	ds_read_b128 v[142:145], v220 offset:46688
	v_add_f32_e32 v231, v231, v34
	v_add_f32_e32 v232, v232, v35
	v_exp_f32_e32 v38, v38
	v_exp_f32_e32 v39, v39
	s_waitcnt lgkmcnt(4)
	v_mfma_f32_32x32x16_bf16 v[66:81], v[146:149], v[102:105], v[66:81]
	ds_read_b128 v[146:149], v220 offset:40064
	v_add_f32_e32 v231, v231, v36
	v_add_f32_e32 v232, v232, v37
	v_exp_f32_e32 v40, v40
	v_exp_f32_e32 v41, v41
	v_mfma_f32_32x32x16_bf16 v[82:97], v[150:153], v[102:105], v[82:97]
	ds_read_b128 v[150:153], v220 offset:46720
	v_add_f32_e32 v231, v231, v38
	v_add_f32_e32 v232, v232, v39
	v_add_f32_e32 v231, v231, v40
	v_add_f32_e32 v232, v232, v41
	v_cvt_pk_bf16_f32 v34, v34, v35
	v_cvt_pk_bf16_f32 v35, v36, v37
	s_waitcnt lgkmcnt(4)
	v_mfma_f32_32x32x16_bf16 v[66:81], v[154:157], v[106:109], v[66:81]
	ds_read_b128 v[154:157], v220 offset:40096
	v_cvt_pk_bf16_f32 v36, v38, v39
	v_cvt_pk_bf16_f32 v37, v40, v41
	v_exp_f32_e32 v42, v42
	v_exp_f32_e32 v43, v43
	v_mfma_f32_32x32x16_bf16 v[82:97], v[158:161], v[106:109], v[82:97]
	ds_read_b128 v[158:161], v220 offset:46752
	v_exp_f32_e32 v44, v44
	v_exp_f32_e32 v45, v45
	v_add_f32_e32 v231, v231, v42
	v_add_f32_e32 v232, v232, v43
	s_waitcnt lgkmcnt(4)
	v_mfma_f32_32x32x16_bf16 v[66:81], v[138:141], v[110:113], v[66:81]
	ds_read_b128 v[162:165], v221 offset:18432
	v_exp_f32_e32 v46, v46
	v_exp_f32_e32 v47, v47
	v_add_f32_e32 v231, v231, v44
	v_add_f32_e32 v232, v232, v45
	v_exp_f32_e32 v48, v48
	v_mfma_f32_32x32x16_bf16 v[82:97], v[142:145], v[110:113], v[82:97]
	ds_read_b128 v[166:169], v221 offset:23040
	v_exp_f32_e32 v49, v49
	v_add_f32_e32 v231, v231, v46
	v_add_f32_e32 v232, v232, v47
	v_add_f32_e32 v231, v231, v48
	s_waitcnt lgkmcnt(4)
	v_mfma_f32_32x32x16_bf16 v[66:81], v[146:149], v[114:117], v[66:81]
	ds_read_b128 v[170:173], v221 offset:18464
	v_add_f32_e32 v232, v232, v49
	v_cvt_pk_bf16_f32 v42, v42, v43
	v_cvt_pk_bf16_f32 v43, v44, v45
	v_cvt_pk_bf16_f32 v44, v46, v47
	v_cvt_pk_bf16_f32 v45, v48, v49
	v_exp_f32_e32 v50, v50
	v_mfma_f32_32x32x16_bf16 v[82:97], v[150:153], v[114:117], v[82:97]
	ds_read_b128 v[174:177], v221 offset:23072
	v_exp_f32_e32 v51, v51
	v_exp_f32_e32 v52, v52
	v_exp_f32_e32 v53, v53
	s_waitcnt lgkmcnt(4)
	v_mfma_f32_32x32x16_bf16 v[66:81], v[154:157], v[118:121], v[66:81]
	ds_read_b128 v[180:183], v221 offset:18496
	v_add_f32_e32 v231, v231, v50
	v_add_f32_e32 v232, v232, v51
	v_exp_f32_e32 v54, v54
	v_exp_f32_e32 v55, v55
	v_mfma_f32_32x32x16_bf16 v[82:97], v[158:161], v[118:121], v[82:97]
	ds_read_b128 v[184:187], v221 offset:23104
	v_add_f32_e32 v231, v231, v52
	v_add_f32_e32 v232, v232, v53
	v_exp_f32_e32 v56, v56
	v_exp_f32_e32 v57, v57
	s_waitcnt lgkmcnt(4)
	v_mfma_f32_32x32x16_bf16 v[2:17], v[162:165], v[34:37], v[2:17]
	ds_read_b128 v[188:191], v221 offset:18528
	v_add_f32_e32 v231, v231, v54
	v_add_f32_e32 v232, v232, v55
	v_add_f32_e32 v231, v231, v56
	v_add_f32_e32 v232, v232, v57
	v_cvt_pk_bf16_f32 v50, v50, v51
	v_cvt_pk_bf16_f32 v51, v52, v53
	v_cvt_pk_bf16_f32 v52, v54, v55
	v_mfma_f32_32x32x16_bf16 v[18:33], v[166:169], v[34:37], v[18:33]
	ds_read_b128 v[192:195], v221 offset:23136
	v_cvt_pk_bf16_f32 v53, v56, v57
	v_exp_f32_e32 v58, v58
	v_exp_f32_e32 v59, v59
	v_exp_f32_e32 v60, v60
	s_waitcnt lgkmcnt(4)
	v_mfma_f32_32x32x16_bf16 v[2:17], v[170:173], v[42:45], v[2:17]
	v_exp_f32_e32 v61, v61
	v_add_f32_e32 v231, v231, v58
	v_add_f32_e32 v232, v232, v59
	v_exp_f32_e32 v62, v62
	v_mfma_f32_32x32x16_bf16 v[18:33], v[174:177], v[42:45], v[18:33]
	v_exp_f32_e32 v63, v63
	v_add_f32_e32 v231, v231, v60
	v_add_f32_e32 v232, v232, v61
	v_exp_f32_e32 v64, v64
	s_waitcnt lgkmcnt(2)
	v_mfma_f32_32x32x16_bf16 v[2:17], v[180:183], v[50:53], v[2:17]
	v_exp_f32_e32 v65, v65
	v_add_f32_e32 v231, v231, v62
	v_add_f32_e32 v232, v232, v63
	v_add_f32_e32 v231, v231, v64
	v_add_f32_e32 v232, v232, v65
	v_mfma_f32_32x32x16_bf16 v[18:33], v[184:187], v[50:53], v[18:33]
	v_cvt_pk_bf16_f32 v58, v58, v59
	v_cvt_pk_bf16_f32 v59, v60, v61
	v_cvt_pk_bf16_f32 v60, v62, v63
	v_cvt_pk_bf16_f32 v61, v64, v65
	v_max3_f32 v234, v66, v67, v68
	v_max3_f32 v235, v82, v83, v84
	s_waitcnt lgkmcnt(0)
	v_mfma_f32_32x32x16_bf16 v[2:17], v[188:191], v[58:61], v[2:17]
	v_max3_f32 v234, v234, v69, v70
	v_max3_f32 v235, v235, v85, v86
	v_max3_f32 v234, v234, v71, v72
	v_max3_f32 v235, v235, v87, v88
	v_max3_f32 v234, v234, v73, v74
	v_max3_f32 v235, v235, v89, v90
	v_max3_f32 v234, v234, v75, v76
	v_mfma_f32_32x32x16_bf16 v[18:33], v[192:195], v[58:61], v[18:33]
	v_max3_f32 v235, v235, v91, v92
	v_max3_f32 v234, v234, v77, v78
	v_max3_f32 v235, v235, v93, v94
	v_max3_f32 v234, v234, v79, v80
	v_max3_f32 v235, v235, v95, v96
	v_max3_f32 v234, v234, v81, v97
	v_max_f32_e32 v234, v234, v235
	v_mov_b32_e32 v235, v234
	s_nop 1
	v_permlane32_swap_b32_e32 v234, v235
	v_max_f32_e32 v233, v234, v235
	v_cmp_lt_f32_e32 vcc, 4.0, v233
	s_cbranch_vccz .Lmls_nr_t2
	s_nop 15
	v_max_f32_e32 v234, 0, v233
	v_exp_f32_e64 v235, -v234
	v_add_f32_e32 v230, v230, v234
	v_sub_f32_e32 v66, v66, v234
	v_sub_f32_e32 v67, v67, v234
	v_sub_f32_e32 v68, v68, v234
	v_sub_f32_e32 v69, v69, v234
	v_sub_f32_e32 v70, v70, v234
	v_sub_f32_e32 v71, v71, v234
	v_sub_f32_e32 v72, v72, v234
	v_sub_f32_e32 v73, v73, v234
	v_sub_f32_e32 v74, v74, v234
	v_sub_f32_e32 v75, v75, v234
	v_sub_f32_e32 v76, v76, v234
	v_sub_f32_e32 v77, v77, v234
	v_sub_f32_e32 v78, v78, v234
	v_sub_f32_e32 v79, v79, v234
	v_sub_f32_e32 v80, v80, v234
	v_sub_f32_e32 v81, v81, v234
	v_sub_f32_e32 v82, v82, v234
	v_sub_f32_e32 v83, v83, v234
	v_sub_f32_e32 v84, v84, v234
	v_sub_f32_e32 v85, v85, v234
	v_sub_f32_e32 v86, v86, v234
	v_sub_f32_e32 v87, v87, v234
	v_sub_f32_e32 v88, v88, v234
	v_sub_f32_e32 v89, v89, v234
	v_sub_f32_e32 v90, v90, v234
	v_sub_f32_e32 v91, v91, v234
	v_sub_f32_e32 v92, v92, v234
	v_sub_f32_e32 v93, v93, v234
	v_sub_f32_e32 v94, v94, v234
	v_sub_f32_e32 v95, v95, v234
	v_sub_f32_e32 v96, v96, v234
	v_sub_f32_e32 v97, v97, v234
	v_mul_f32_e32 v231, v231, v235
	v_mul_f32_e32 v232, v232, v235
	v_mul_f32_e32 v2, v2, v235
	v_mul_f32_e32 v3, v3, v235
	v_mul_f32_e32 v4, v4, v235
	v_mul_f32_e32 v5, v5, v235
	v_mul_f32_e32 v6, v6, v235
	v_mul_f32_e32 v7, v7, v235
	v_mul_f32_e32 v8, v8, v235
	v_mul_f32_e32 v9, v9, v235
	v_mul_f32_e32 v10, v10, v235
	v_mul_f32_e32 v11, v11, v235
	v_mul_f32_e32 v12, v12, v235
	v_mul_f32_e32 v13, v13, v235
	v_mul_f32_e32 v14, v14, v235
	v_mul_f32_e32 v15, v15, v235
	v_mul_f32_e32 v16, v16, v235
	v_mul_f32_e32 v17, v17, v235
	v_mul_f32_e32 v18, v18, v235
	v_mul_f32_e32 v19, v19, v235
	v_mul_f32_e32 v20, v20, v235
	v_mul_f32_e32 v21, v21, v235
	v_mul_f32_e32 v22, v22, v235
	v_mul_f32_e32 v23, v23, v235
	v_mul_f32_e32 v24, v24, v235
	v_mul_f32_e32 v25, v25, v235
	v_mul_f32_e32 v26, v26, v235
	v_mul_f32_e32 v27, v27, v235
	v_mul_f32_e32 v28, v28, v235
	v_mul_f32_e32 v29, v29, v235
	v_mul_f32_e32 v30, v30, v235
	v_mul_f32_e32 v31, v31, v235
	v_mul_f32_e32 v32, v32, v235
	v_mul_f32_e32 v33, v33, v235
	v_sub_f32_e32 v122, 0, v230
	v_mov_b32_e32 v123, v122
	v_mov_b32_e32 v124, v122
	v_mov_b32_e32 v125, v122
	v_mov_b32_e32 v126, v122
	v_mov_b32_e32 v127, v122
	v_mov_b32_e32 v128, v122
	v_mov_b32_e32 v129, v122
	v_mov_b32_e32 v130, v122
	v_mov_b32_e32 v131, v122
	v_mov_b32_e32 v132, v122
	v_mov_b32_e32 v133, v122
	v_mov_b32_e32 v134, v122
	v_mov_b32_e32 v135, v122
	v_mov_b32_e32 v136, v122
	v_mov_b32_e32 v137, v122
